# s_setprio 2 for code between GEMM k-loops (epilogue + next prologue), reset to 0 at phase end
# speedup vs baseline: 1.0122x; 1.0122x over previous
; #define G_STORE(ST, S, unused) do { char* d_ = smem + (ST) * STAGE; \
;     *(uint4*)(d_ + alo[0]) = S##a0; *(uint4*)(d_ + alo[1]) = S##a1; *(uint4*)(d_ + alo[2]) = S##a2; *(uint4*)(d_ + alo[3]) = S##a3; \
;     *(uint4*)(d_ + blo[0]) = S##b0; *(uint4*)(d_ + blo[1]) = S##b1; \
;     if (NBCH == 4) { *(uint4*)(d_ + blo[NBCH - 2]) = S##b2; *(uint4*)(d_ + blo[NBCH - 1]) = S##b3; } } while (0)
; template <int NJ, class RowA>
; DI void gemm_main(f32x16 (&acc)[2][NJ], const bf16_t* __restrict__ A, RowA rowA, size_t kstrideA, int m0, int Mmax,
;                   const bf16_t* __restrict__ Bt, size_t ldb, int n0, int nk, char* smem) {
;     ...
;   __syncthreads();
;   G_LOAD(x0, 0, 0);
;   G_LOAD(x1, 0, 1);
;   G_STORE(0, x0, 0);
;   __syncthreads();
; #pragma unroll 1
;   for (int kt = 0; kt < nk; kt += 2) {
;     G_LOAD(x0, 0, (kt + 2 < nk ? kt + 2 : nk - 1));
;     G_COMPUTE(0);
;     G_STORE(1, x1, 0);
;     __syncthreads();
;     G_LOAD(x1, 0, (kt + 3 < nk ? kt + 3 : nk - 1));
;     G_COMPUTE(1);
;     G_STORE(0, x0, 0);
;     __syncthreads();
.Lpeel_tail_12:
	ds_read_b128 v[166:169], v0
	ds_read_b128 v[170:173], v139 offset:18432
	ds_read_b128 v[174:177], v139 offset:23040
	ds_read_b128 v[178:181], v0 offset:4608
	s_add_i32 s4, s3, 4
	s_min_u32 s4, s4, 15
	s_lshl_b32 s14, s4, 7
	v_lshl_add_u64 v[98:99], v[122:123], 0, s[14:15]
	v_lshl_add_u64 v[102:103], v[124:125], 0, s[14:15]
	v_lshl_add_u64 v[106:107], v[126:127], 0, s[14:15]
	v_lshl_add_u64 v[110:111], v[128:129], 0, s[14:15]
	v_lshl_add_u64 v[114:115], v[130:131], 0, s[14:15]
	v_lshl_add_u64 v[118:119], v[132:133], 0, s[14:15]
	s_add_i32 s3, s3, 2
	v_lshl_add_u64 v[158:159], v[134:135], 0, s[14:15]
	v_lshl_add_u64 v[160:161], v[136:137], 0, s[14:15]
	s_setprio 1
	ds_read_b128 v[182:185], v0 offset:32
	ds_read_b128 v[186:189], v139 offset:18464
	ds_read_b128 v[190:193], v139 offset:23072
	ds_read_b128 v[194:197], v0 offset:4640
	s_waitcnt lgkmcnt(4)
	v_mfma_f32_32x32x16_bf16 v[50:65], v[166:169], v[170:173], v[50:65]
	v_mfma_f32_32x32x16_bf16 v[34:49], v[166:169], v[174:177], v[34:49]
	v_mfma_f32_32x32x16_bf16 v[18:33], v[178:181], v[170:173], v[18:33]
	v_mfma_f32_32x32x16_bf16 v[2:17], v[178:181], v[174:177], v[2:17]
	ds_read_b128 v[166:169], v0 offset:64
	ds_read_b128 v[170:173], v139 offset:18496
	ds_read_b128 v[174:177], v139 offset:23104
	ds_read_b128 v[178:181], v0 offset:4672
	s_waitcnt lgkmcnt(4)
	v_mfma_f32_32x32x16_bf16 v[50:65], v[182:185], v[186:189], v[50:65]
	v_mfma_f32_32x32x16_bf16 v[34:49], v[182:185], v[190:193], v[34:49]
	v_mfma_f32_32x32x16_bf16 v[18:33], v[194:197], v[186:189], v[18:33]
	v_mfma_f32_32x32x16_bf16 v[2:17], v[194:197], v[190:193], v[2:17]
	ds_read_b128 v[182:185], v0 offset:96
	ds_read_b128 v[186:189], v139 offset:18528
	ds_read_b128 v[190:193], v139 offset:23136
	ds_read_b128 v[194:197], v0 offset:4704
	s_waitcnt lgkmcnt(4)
	v_mfma_f32_32x32x16_bf16 v[50:65], v[166:169], v[170:173], v[50:65]
	s_waitcnt vmcnt(0)
	ds_write_b128 v138, v[78:81] offset:36864
	v_mfma_f32_32x32x16_bf16 v[34:49], v[166:169], v[174:177], v[34:49]
	ds_write_b128 v140, v[86:89] offset:36864
	v_mfma_f32_32x32x16_bf16 v[18:33], v[178:181], v[170:173], v[18:33]
	ds_write_b128 v142, v[90:93] offset:36864
	v_mfma_f32_32x32x16_bf16 v[2:17], v[178:181], v[174:177], v[2:17]
	ds_write_b128 v144, v[94:97] offset:36864
	s_waitcnt lgkmcnt(4)
	v_mfma_f32_32x32x16_bf16 v[50:65], v[182:185], v[186:189], v[50:65]
	ds_write_b128 v138, v[74:77] offset:55296
	v_mfma_f32_32x32x16_bf16 v[34:49], v[182:185], v[190:193], v[34:49]
	ds_write_b128 v140, v[82:85] offset:55296
	v_mfma_f32_32x32x16_bf16 v[18:33], v[194:197], v[186:189], v[18:33]
	ds_write_b128 v142, v[66:69] offset:55296
	v_mfma_f32_32x32x16_bf16 v[2:17], v[194:197], v[190:193], v[2:17]
	ds_write_b128 v144, v[70:73] offset:55296
	s_setprio 0
	s_min_u32 s4, s3, 12
	s_lshl_b32 s14, s4, 7
	v_lshl_add_u64 v[66:67], v[122:123], 0, s[14:15]
	v_lshl_add_u64 v[68:69], v[124:125], 0, s[14:15]
	v_lshl_add_u64 v[70:71], v[126:127], 0, s[14:15]
	v_lshl_add_u64 v[72:73], v[128:129], 0, s[14:15]
	v_lshl_add_u64 v[74:75], v[130:131], 0, s[14:15]
	v_lshl_add_u64 v[82:83], v[132:133], 0, s[14:15]
	s_waitcnt lgkmcnt(0)
	s_barrier
	ds_read_b128 v[166:169], v0 offset:36864
	ds_read_b128 v[170:173], v139 offset:55296
	ds_read_b128 v[174:177], v139 offset:59904
	ds_read_b128 v[178:181], v0 offset:41472
	v_lshl_add_u64 v[154:155], v[134:135], 0, s[14:15]
	v_lshl_add_u64 v[156:157], v[136:137], 0, s[14:15]
	s_setprio 1
	ds_read_b128 v[182:185], v0 offset:36896
	ds_read_b128 v[186:189], v139 offset:55328
	ds_read_b128 v[190:193], v139 offset:59936
	ds_read_b128 v[194:197], v0 offset:41504
	s_waitcnt lgkmcnt(4)
	v_mfma_f32_32x32x16_bf16 v[50:65], v[166:169], v[170:173], v[50:65]
	v_mfma_f32_32x32x16_bf16 v[34:49], v[166:169], v[174:177], v[34:49]
	v_mfma_f32_32x32x16_bf16 v[18:33], v[178:181], v[170:173], v[18:33]
	v_mfma_f32_32x32x16_bf16 v[2:17], v[178:181], v[174:177], v[2:17]
	ds_read_b128 v[166:169], v0 offset:36928
	ds_read_b128 v[170:173], v139 offset:55360
	ds_read_b128 v[174:177], v139 offset:59968
	ds_read_b128 v[178:181], v0 offset:41536
	s_waitcnt lgkmcnt(4)
	v_mfma_f32_32x32x16_bf16 v[50:65], v[182:185], v[186:189], v[50:65]
	v_mfma_f32_32x32x16_bf16 v[34:49], v[182:185], v[190:193], v[34:49]
	v_mfma_f32_32x32x16_bf16 v[18:33], v[194:197], v[186:189], v[18:33]
	v_mfma_f32_32x32x16_bf16 v[2:17], v[194:197], v[190:193], v[2:17]
	ds_read_b128 v[182:185], v0 offset:36960
	ds_read_b128 v[186:189], v139 offset:55392
	ds_read_b128 v[190:193], v139 offset:60000
	ds_read_b128 v[194:197], v0 offset:41568
	s_waitcnt lgkmcnt(4)
	v_mfma_f32_32x32x16_bf16 v[50:65], v[166:169], v[170:173], v[50:65]
	v_mfma_f32_32x32x16_bf16 v[34:49], v[166:169], v[174:177], v[34:49]
	v_mfma_f32_32x32x16_bf16 v[18:33], v[178:181], v[170:173], v[18:33]
	v_mfma_f32_32x32x16_bf16 v[2:17], v[178:181], v[174:177], v[2:17]
	s_waitcnt lgkmcnt(0)
	v_mfma_f32_32x32x16_bf16 v[50:65], v[182:185], v[186:189], v[50:65]
	v_mfma_f32_32x32x16_bf16 v[34:49], v[182:185], v[190:193], v[34:49]
	v_mfma_f32_32x32x16_bf16 v[18:33], v[194:197], v[186:189], v[18:33]
	v_mfma_f32_32x32x16_bf16 v[2:17], v[194:197], v[190:193], v[2:17]
	s_setprio 0
	s_cmp_lt_u32 s3, 14
	s_waitcnt lgkmcnt(0)
	s_barrier
; #define TIDX (tid_launder())
; DI int crow(int reg, int hh) { return (reg & 3) + 8 * (reg >> 2) + 4 * hh; }
; template <int NJ>
; DI void acc_to_ct(const f32x16 (&acc)[2][NJ], float* Ct) {
;   const int lane = TIDX & 63, wid = TIDX >> 6, wm = wid >> 1, wn = wid & 1;
;   const int r = lane & 31, hh = lane >> 5;
; #pragma unroll
;   for (int i = 0; i < 2; ++i)
; #pragma unroll
;     for (int j = 0; j < NJ; ++j)
; #pragma unroll
;       for (int e = 0; e < 16; ++e) Ct[(wm * 64 + i * 32 + crow(e, hh)) * 132 + wn * 32 * NJ + j * 32 + r] = acc[i][j][e];
;   __syncthreads();
; DI void outproj_tile(const Params& p, int l, int mt, int tn, char* smem) {
;     ...
;   const float* xo = l == 0 ? p.x_in : p.out;
;   {
;     const int tid = TIDX, c = (tid & 31) * 4, row0 = tid >> 5;
;     float4 xa[16];
; #pragma unroll
;     for (int q = 0; q < 16; ++q) xa[q] = *(const float4*)(xo + (size_t)(m0 + row0 + 8 * q) * 1024 + tn * 128 + c);
	s_setprio 2
	v_mov_b32_e32 v0, v230
	s_waitcnt vmcnt(1)
	v_mov_b32_e32 v66, v230
	v_and_b32_e32 v67, 31, v0
	v_lshrrev_b32_e32 v0, 3, v0
	v_and_b32_e32 v0, 4, v0
	v_lshrrev_b32_e32 v68, 1, v66
	v_and_or_b32 v0, v68, s47, v0
	v_and_or_b32 v66, v66, 64, v67
	v_mul_lo_u32 v0, v0, s79
	v_lshl_add_u32 v0, v66, 2, v0
	ds_write2_b32 v0, v50, v34 offset1:32
	ds_write2_b32 v0, v51, v35 offset0:132 offset1:164
	v_add_u32_e32 v34, 0x400, v0
	ds_write2_b32 v34, v52, v36 offset0:8 offset1:40
	ds_write2_b32 v34, v53, v37 offset0:140 offset1:172
	v_add_u32_e32 v34, 0x1000, v0
	ds_write2_b32 v34, v54, v38 offset0:32 offset1:64
	ds_write2_b32 v34, v55, v39 offset0:164 offset1:196
	v_add_u32_e32 v34, 0x1400, v0
	ds_write2_b32 v34, v56, v40 offset0:40 offset1:72
	ds_write2_b32 v34, v57, v41 offset0:172 offset1:204
	v_add_u32_e32 v34, 0x2000, v0
	ds_write2_b32 v34, v58, v42 offset0:64 offset1:96
	ds_write2_b32 v34, v59, v43 offset0:196 offset1:228
	v_add_u32_e32 v34, 0x2400, v0
	ds_write2_b32 v34, v60, v44 offset0:72 offset1:104
	ds_write2_b32 v34, v61, v45 offset0:204 offset1:236
	v_add_u32_e32 v34, 0x3000, v0
	ds_write2_b32 v34, v62, v46 offset0:96 offset1:128
	v_add_u32_e32 v34, 0x3200, v0
	ds_write2_b32 v34, v63, v47 offset0:100 offset1:132
	v_add_u32_e32 v34, 0x3400, v0
	ds_write2_b32 v34, v64, v48 offset0:104 offset1:136
	v_add_u32_e32 v34, 0x3600, v0
	ds_write2_b32 v34, v65, v49 offset0:108 offset1:140
	v_add_u32_e32 v34, 0x4000, v0
	ds_write2_b32 v34, v18, v2 offset0:128 offset1:160
	v_add_u32_e32 v2, 0x4400, v0
	ds_write2_b32 v2, v19, v3 offset0:4 offset1:36
	ds_write2_b32 v2, v20, v4 offset0:136 offset1:168
	v_add_u32_e32 v2, 0x4800, v0
	ds_write2_b32 v2, v21, v5 offset0:12 offset1:44
	v_add_u32_e32 v2, 0x5000, v0
	ds_write2_b32 v2, v22, v6 offset0:160 offset1:192
	v_add_u32_e32 v2, 0x5400, v0
	ds_write2_b32 v2, v23, v7 offset0:36 offset1:68
	ds_write2_b32 v2, v24, v8 offset0:168 offset1:200
	v_add_u32_e32 v2, 0x5800, v0
	ds_write2_b32 v2, v25, v9 offset0:44 offset1:76
	v_add_u32_e32 v2, 0x6000, v0
	ds_write2_b32 v2, v26, v10 offset0:192 offset1:224
	v_add_u32_e32 v2, 0x6400, v0
	ds_write2_b32 v2, v27, v11 offset0:68 offset1:100
	ds_write2_b32 v2, v28, v12 offset0:200 offset1:232
	v_add_u32_e32 v2, 0x6800, v0
	ds_write2_b32 v2, v29, v13 offset0:76 offset1:108
	v_add_u32_e32 v2, 0x7200, v0
	ds_write2_b32 v2, v30, v14 offset0:96 offset1:128
	v_add_u32_e32 v2, 0x7400, v0
	ds_write2_b32 v2, v31, v15 offset0:100 offset1:132
	v_add_u32_e32 v2, 0x7600, v0
	v_add_u32_e32 v0, 0x7800, v0
	ds_write2_b32 v0, v33, v17 offset0:108 offset1:140
	v_mov_b32_e32 v0, v230
	ds_write2_b32 v2, v32, v16 offset0:104 offset1:136
	s_waitcnt lgkmcnt(0)
	s_barrier
	s_lshl_b32 s14, s2, 2
	v_ashrrev_i32_e32 v68, 5, v0
	v_readlane_b32 s2, v254, 3
	v_add_u32_e32 v2, s1, v68
	v_readlane_b32 s3, v254, 4
	s_add_u32 s2, s2, s14
	v_lshlrev_b32_e32 v0, 4, v0
	s_addc_u32 s3, s3, 0
	v_and_b32_e32 v0, 0x1f0, v0
	v_ashrrev_i32_e32 v3, 31, v2
	v_lshl_add_u64 v[4:5], s[2:3], 0, v[0:1]
	v_lshlrev_b64 v[8:9], 12, v[2:3]
	s_mov_b64 s[2:3], 0x18000
	v_lshl_add_u64 v[20:21], v[8:9], 0, s[2:3]
	s_mov_b64 s[2:3], 0x20000
	v_lshl_add_u64 v[24:25], v[8:9], 0, s[2:3]
	s_mov_b64 s[2:3], 0x28000
	v_lshl_add_u64 v[28:29], v[8:9], 0, s[2:3]
	s_mov_b64 s[2:3], 0x30000
	v_lshl_add_u64 v[32:33], v[8:9], 0, s[2:3]
	s_mov_b64 s[2:3], 0x38000
	v_lshl_add_u64 v[36:37], v[8:9], 0, s[2:3]
	s_mov_b64 s[2:3], 0x40000
	v_lshl_add_u64 v[40:41], v[8:9], 0, s[2:3]
	s_mov_b64 s[2:3], 0x48000
	v_lshl_add_u64 v[44:45], v[8:9], 0, s[2:3]
	s_mov_b64 s[2:3], 0x50000
	v_lshl_add_u64 v[48:49], v[8:9], 0, s[2:3]
	s_mov_b64 s[2:3], 0x58000
	v_lshl_add_u64 v[52:53], v[8:9], 0, s[2:3]
	s_mov_b64 s[2:3], 0x60000
	v_lshl_add_u64 v[56:57], v[8:9], 0, s[2:3]
	s_mov_b64 s[2:3], 0x68000
	v_lshl_add_u64 v[60:61], v[8:9], 0, s[2:3]
	s_mov_b64 s[2:3], 0x70000
	v_lshl_add_u64 v[64:65], v[8:9], 0, s[2:3]
	s_mov_b64 s[2:3], 0x78000
	v_readlane_b32 s16, v252, 9
	v_lshl_add_u64 v[12:13], v[8:9], 0, s[48:49]
	v_lshl_add_u64 v[16:17], v[8:9], 0, s[40:41]
	v_lshl_add_u64 v[66:67], v[8:9], 0, s[2:3]
	v_readlane_b32 s22, v252, 15
	v_readlane_b32 s23, v252, 16
	v_lshl_add_u64 v[62:63], v[4:5], 0, v[8:9]
	v_lshl_add_u64 v[58:59], v[4:5], 0, v[12:13]
	v_lshl_add_u64 v[54:55], v[4:5], 0, v[16:17]
	v_lshl_add_u64 v[50:51], v[4:5], 0, v[20:21]
	v_lshl_add_u64 v[46:47], v[4:5], 0, v[24:25]
	v_lshl_add_u64 v[42:43], v[4:5], 0, v[28:29]
	v_lshl_add_u64 v[38:39], v[4:5], 0, v[32:33]
	v_lshl_add_u64 v[34:35], v[4:5], 0, v[36:37]
	v_lshl_add_u64 v[30:31], v[4:5], 0, v[40:41]
	v_lshl_add_u64 v[26:27], v[4:5], 0, v[44:45]
	v_lshl_add_u64 v[22:23], v[4:5], 0, v[48:49]
	v_lshl_add_u64 v[18:19], v[4:5], 0, v[52:53]
	v_lshl_add_u64 v[14:15], v[4:5], 0, v[56:57]
	v_lshl_add_u64 v[10:11], v[4:5], 0, v[60:61]
	v_lshl_add_u64 v[6:7], v[4:5], 0, v[64:65]
	v_lshl_add_u64 v[2:3], v[4:5], 0, v[66:67]
	v_lshl_add_u64 v[4:5], s[22:23], 0, v[8:9]
	v_lshl_add_u64 v[4:5], v[4:5], 0, s[14:15]
	v_lshl_add_u64 v[96:97], v[4:5], 0, v[0:1]
	v_lshl_add_u64 v[4:5], s[22:23], 0, v[12:13]
	v_lshl_add_u64 v[4:5], v[4:5], 0, s[14:15]
	v_lshl_add_u64 v[94:95], v[4:5], 0, v[0:1]
	v_lshl_add_u64 v[4:5], s[22:23], 0, v[16:17]
	v_lshl_add_u64 v[4:5], v[4:5], 0, s[14:15]
	v_lshl_add_u64 v[92:93], v[4:5], 0, v[0:1]
	v_lshl_add_u64 v[4:5], s[22:23], 0, v[20:21]
	v_lshl_add_u64 v[4:5], v[4:5], 0, s[14:15]
	v_lshl_add_u64 v[90:91], v[4:5], 0, v[0:1]
	v_lshl_add_u64 v[4:5], s[22:23], 0, v[24:25]
	v_lshl_add_u64 v[4:5], v[4:5], 0, s[14:15]
	v_lshl_add_u64 v[88:89], v[4:5], 0, v[0:1]
	v_lshl_add_u64 v[4:5], s[22:23], 0, v[28:29]
	v_lshl_add_u64 v[4:5], v[4:5], 0, s[14:15]
	v_lshl_add_u64 v[86:87], v[4:5], 0, v[0:1]
	v_lshl_add_u64 v[4:5], s[22:23], 0, v[32:33]
	v_lshl_add_u64 v[4:5], v[4:5], 0, s[14:15]
	v_lshl_add_u64 v[84:85], v[4:5], 0, v[0:1]
	v_lshl_add_u64 v[4:5], s[22:23], 0, v[36:37]
	v_lshl_add_u64 v[4:5], v[4:5], 0, s[14:15]
	v_lshl_add_u64 v[82:83], v[4:5], 0, v[0:1]
	v_lshl_add_u64 v[4:5], s[22:23], 0, v[40:41]
	v_lshl_add_u64 v[4:5], v[4:5], 0, s[14:15]
	v_lshl_add_u64 v[80:81], v[4:5], 0, v[0:1]
	v_lshl_add_u64 v[4:5], s[22:23], 0, v[44:45]
	v_lshl_add_u64 v[4:5], v[4:5], 0, s[14:15]
	v_lshl_add_u64 v[78:79], v[4:5], 0, v[0:1]
	v_lshl_add_u64 v[4:5], s[22:23], 0, v[48:49]
	v_lshl_add_u64 v[4:5], v[4:5], 0, s[14:15]
	v_lshl_add_u64 v[76:77], v[4:5], 0, v[0:1]
	v_lshl_add_u64 v[4:5], s[22:23], 0, v[52:53]
	v_lshl_add_u64 v[4:5], v[4:5], 0, s[14:15]
	v_lshl_add_u64 v[74:75], v[4:5], 0, v[0:1]
	v_lshl_add_u64 v[4:5], s[22:23], 0, v[56:57]
	v_lshl_add_u64 v[4:5], v[4:5], 0, s[14:15]
	s_waitcnt vmcnt(0)
; #define TIDX (tid_launder())
; DI void outproj_tile(const Params& p, int l, int mt, int tn, char* smem) {
;     ...
;     const int tid = TIDX, c = (tid & 31) * 4, row0 = tid >> 5;
;     float4 xa[16];
; #pragma unroll
;     for (int q = 0; q < 16; ++q) xa[q] = *(const float4*)(xo + (size_t)(m0 + row0 + 8 * q) * 1024 + tn * 128 + c);
; #pragma unroll
;     for (int q = 0; q < 16; ++q) {
;       const float4 cc = *(const float4*)(Ct + (row0 + 8 * q) * 132 + c);
;       *(float4*)(p.out + (size_t)(m0 + row0 + 8 * q) * 1024 + tn * 128 + c) = make_float4(xa[q].x + cc.x, xa[q].y + cc.y, xa[q].z + cc.z, xa[q].w + cc.w);
;     }
;   }
;   __syncthreads();
	v_lshl_add_u64 v[72:73], v[4:5], 0, v[0:1]
	v_lshl_add_u64 v[4:5], s[22:23], 0, v[60:61]
	v_lshl_add_u64 v[4:5], v[4:5], 0, s[14:15]
	v_lshl_add_u64 v[70:71], v[4:5], 0, v[0:1]
	v_lshl_add_u64 v[4:5], s[22:23], 0, v[64:65]
	v_lshl_add_u64 v[4:5], v[4:5], 0, s[14:15]
	v_mad_u64_u32 v[98:99], s[2:3], v68, s79, v[0:1]
	v_lshl_add_u64 v[68:69], v[4:5], 0, v[0:1]
	v_lshl_add_u64 v[4:5], s[22:23], 0, v[66:67]
	v_lshl_add_u64 v[4:5], v[4:5], 0, s[14:15]
	v_lshl_add_u64 v[66:67], v[4:5], 0, v[0:1]
	global_load_dwordx4 v[2:5], v[2:3], off
	ds_read_b128 v[100:103], v98 offset:63360
	global_load_dwordx4 v[6:9], v[6:7], off
	v_readlane_b32 s1, v250, 60
	global_load_dwordx4 v[10:13], v[10:11], off
	s_add_i32 s0, s0, s1
	global_load_dwordx4 v[14:17], v[14:15], off
	s_cmpk_gt_u32 s0, 0xff
	global_load_dwordx4 v[18:21], v[18:19], off
	v_readlane_b32 s17, v252, 10
	global_load_dwordx4 v[22:25], v[22:23], off
	v_readlane_b32 s18, v252, 11
	global_load_dwordx4 v[26:29], v[26:27], off
	v_readlane_b32 s19, v252, 12
	global_load_dwordx4 v[30:33], v[30:31], off
	v_readlane_b32 s20, v252, 13
	global_load_dwordx4 v[34:37], v[34:35], off
	v_readlane_b32 s21, v252, 14
	global_load_dwordx4 v[38:41], v[38:39], off
	v_readlane_b32 s24, v252, 17
	global_load_dwordx4 v[42:45], v[42:43], off
	v_readlane_b32 s25, v252, 18
	global_load_dwordx4 v[46:49], v[46:47], off
	v_readlane_b32 s26, v252, 19
	global_load_dwordx4 v[50:53], v[50:51], off
	v_readlane_b32 s27, v252, 20
	global_load_dwordx4 v[54:57], v[54:55], off
	v_readlane_b32 s28, v252, 21
	global_load_dwordx4 v[58:61], v[58:59], off
	v_readlane_b32 s29, v252, 22
	global_load_dwordx4 v[62:65], v[62:63], off
	v_readlane_b32 s30, v252, 23
	v_readlane_b32 s31, v252, 24
	s_waitcnt vmcnt(15) lgkmcnt(0)
	v_pk_add_f32 v[2:3], v[2:3], v[100:101]
	v_pk_add_f32 v[4:5], v[4:5], v[102:103]
	ds_read_b128 v[100:103], v98 offset:59136
	s_waitcnt vmcnt(14) lgkmcnt(0)
	v_pk_add_f32 v[6:7], v[6:7], v[100:101]
	v_pk_add_f32 v[8:9], v[8:9], v[102:103]
	ds_read_b128 v[100:103], v98 offset:54912
	s_waitcnt vmcnt(13) lgkmcnt(0)
	v_pk_add_f32 v[10:11], v[10:11], v[100:101]
	v_pk_add_f32 v[12:13], v[12:13], v[102:103]
	ds_read_b128 v[100:103], v98 offset:50688
	s_waitcnt vmcnt(12) lgkmcnt(0)
	v_pk_add_f32 v[14:15], v[14:15], v[100:101]
	v_pk_add_f32 v[16:17], v[16:17], v[102:103]
	ds_read_b128 v[100:103], v98 offset:46464
	s_waitcnt vmcnt(11) lgkmcnt(0)
	v_pk_add_f32 v[18:19], v[18:19], v[100:101]
	v_pk_add_f32 v[20:21], v[20:21], v[102:103]
	ds_read_b128 v[100:103], v98 offset:42240
	s_waitcnt vmcnt(10) lgkmcnt(0)
	v_pk_add_f32 v[22:23], v[22:23], v[100:101]
	v_pk_add_f32 v[24:25], v[24:25], v[102:103]
	ds_read_b128 v[100:103], v98 offset:38016
	s_waitcnt vmcnt(9) lgkmcnt(0)
	v_pk_add_f32 v[26:27], v[26:27], v[100:101]
	v_pk_add_f32 v[28:29], v[28:29], v[102:103]
	ds_read_b128 v[100:103], v98 offset:33792
	s_waitcnt vmcnt(8) lgkmcnt(0)
	v_pk_add_f32 v[30:31], v[30:31], v[100:101]
	v_pk_add_f32 v[32:33], v[32:33], v[102:103]
	ds_read_b128 v[100:103], v98 offset:29568
	s_waitcnt vmcnt(7) lgkmcnt(0)
	v_pk_add_f32 v[34:35], v[34:35], v[100:101]
	v_pk_add_f32 v[36:37], v[36:37], v[102:103]
	ds_read_b128 v[100:103], v98 offset:25344
	s_waitcnt vmcnt(6) lgkmcnt(0)
	v_pk_add_f32 v[38:39], v[38:39], v[100:101]
	v_pk_add_f32 v[40:41], v[40:41], v[102:103]
	ds_read_b128 v[100:103], v98 offset:21120
	s_waitcnt vmcnt(5) lgkmcnt(0)
	v_pk_add_f32 v[42:43], v[42:43], v[100:101]
	v_pk_add_f32 v[44:45], v[44:45], v[102:103]
	ds_read_b128 v[100:103], v98 offset:16896
	s_waitcnt vmcnt(4) lgkmcnt(0)
	v_pk_add_f32 v[46:47], v[46:47], v[100:101]
	v_pk_add_f32 v[48:49], v[48:49], v[102:103]
	ds_read_b128 v[100:103], v98 offset:12672
	s_waitcnt vmcnt(3) lgkmcnt(0)
	v_pk_add_f32 v[50:51], v[50:51], v[100:101]
	v_pk_add_f32 v[52:53], v[52:53], v[102:103]
	ds_read_b128 v[100:103], v98 offset:8448
	s_waitcnt vmcnt(2) lgkmcnt(0)
	v_pk_add_f32 v[54:55], v[54:55], v[100:101]
	v_pk_add_f32 v[56:57], v[56:57], v[102:103]
	ds_read_b128 v[100:103], v98 offset:4224
	s_waitcnt vmcnt(1) lgkmcnt(0)
	v_pk_add_f32 v[58:59], v[58:59], v[100:101]
	ds_read_b128 v[98:101], v98
	v_pk_add_f32 v[60:61], v[60:61], v[102:103]
	s_waitcnt vmcnt(0) lgkmcnt(0)
	v_pk_add_f32 v[62:63], v[62:63], v[98:99]
	v_pk_add_f32 v[64:65], v[64:65], v[100:101]
	global_store_dwordx4 v[96:97], v[62:65], off
	global_store_dwordx4 v[94:95], v[58:61], off
	global_store_dwordx4 v[92:93], v[54:57], off
	global_store_dwordx4 v[90:91], v[50:53], off
	global_store_dwordx4 v[88:89], v[46:49], off
	global_store_dwordx4 v[86:87], v[42:45], off
	global_store_dwordx4 v[84:85], v[38:41], off
	global_store_dwordx4 v[82:83], v[34:37], off
	global_store_dwordx4 v[80:81], v[30:33], off
	global_store_dwordx4 v[78:79], v[26:29], off
	global_store_dwordx4 v[76:77], v[22:25], off
	global_store_dwordx4 v[74:75], v[18:21], off
	global_store_dwordx4 v[72:73], v[14:17], off
	global_store_dwordx4 v[70:71], v[10:13], off
	global_store_dwordx4 v[68:69], v[6:9], off
	global_store_dwordx4 v[66:67], v[2:5], off
	s_barrier
	s_cbranch_scc0 .LBB0_11

; #define G_STORE(ST, S, unused) do { char* d_ = smem + (ST) * STAGE; \
;     *(uint4*)(d_ + alo[0]) = S##a0; *(uint4*)(d_ + alo[1]) = S##a1; *(uint4*)(d_ + alo[2]) = S##a2; *(uint4*)(d_ + alo[3]) = S##a3; \
;     *(uint4*)(d_ + blo[0]) = S##b0; *(uint4*)(d_ + blo[1]) = S##b1; \
;     if (NBCH == 4) { *(uint4*)(d_ + blo[NBCH - 2]) = S##b2; *(uint4*)(d_ + blo[NBCH - 1]) = S##b3; } } while (0)
; template <int NJ, class RowA>
; DI void gemm_main(f32x16 (&acc)[2][NJ], const bf16_t* __restrict__ A, RowA rowA, size_t kstrideA, int m0, int Mmax,
;                   const bf16_t* __restrict__ Bt, size_t ldb, int n0, int nk, char* smem) {
;     ...
;   __syncthreads();
;   G_LOAD(x0, 0, 0);
;   G_LOAD(x1, 0, 1);
;   G_STORE(0, x0, 0);
;   __syncthreads();
; #pragma unroll 1
;   for (int kt = 0; kt < nk; kt += 2) {
;     G_LOAD(x0, 0, (kt + 2 < nk ? kt + 2 : nk - 1));
;     G_COMPUTE(0);
;     G_STORE(1, x1, 0);
;     __syncthreads();
;     G_LOAD(x1, 0, (kt + 3 < nk ? kt + 3 : nk - 1));
;     G_COMPUTE(1);
;     G_STORE(0, x0, 0);
;     __syncthreads();
.Lpeel_tail_19:
	ds_read_b128 v[176:179], v0
	ds_read_b128 v[180:183], v71 offset:18432
	ds_read_b128 v[184:187], v0 offset:4608
	s_add_i32 s5, s4, 4
	s_min_u32 s5, s5, 15
	s_lshl_b32 s14, s5, 7
	v_lshl_add_u64 v[78:79], v[58:59], 0, s[14:15]
	v_lshl_add_u64 v[82:83], v[60:61], 0, s[14:15]
	v_lshl_add_u64 v[86:87], v[62:63], 0, s[14:15]
	v_lshl_add_u64 v[122:123], v[64:65], 0, s[14:15]
	v_lshl_add_u64 v[126:127], v[66:67], 0, s[14:15]
	v_lshl_add_u64 v[130:131], v[68:69], 0, s[14:15]
	s_add_i32 s4, s4, 2
	s_setprio 1
	ds_read_b128 v[188:191], v0 offset:32
	ds_read_b128 v[192:195], v71 offset:18464
	ds_read_b128 v[196:199], v0 offset:4640
	s_waitcnt lgkmcnt(3)
	v_mfma_f32_32x32x16_bf16 v[18:33], v[176:179], v[180:183], v[18:33]
	v_mfma_f32_32x32x16_bf16 v[2:17], v[184:187], v[180:183], v[2:17]
	ds_read_b128 v[176:179], v0 offset:64
	ds_read_b128 v[180:183], v71 offset:18496
	ds_read_b128 v[184:187], v0 offset:4672
	s_waitcnt lgkmcnt(3)
	v_mfma_f32_32x32x16_bf16 v[18:33], v[188:191], v[192:195], v[18:33]
	v_mfma_f32_32x32x16_bf16 v[2:17], v[196:199], v[192:195], v[2:17]
	ds_read_b128 v[188:191], v0 offset:96
	ds_read_b128 v[192:195], v71 offset:18528
	ds_read_b128 v[196:199], v0 offset:4704
	s_waitcnt lgkmcnt(3)
	v_mfma_f32_32x32x16_bf16 v[18:33], v[176:179], v[180:183], v[18:33]
	s_waitcnt vmcnt(0)
	ds_write_b128 v70, v[34:37] offset:27648
	ds_write_b128 v72, v[38:41] offset:27648
	v_mfma_f32_32x32x16_bf16 v[2:17], v[184:187], v[180:183], v[2:17]
	ds_write_b128 v74, v[42:45] offset:27648
	s_waitcnt lgkmcnt(3)
	v_mfma_f32_32x32x16_bf16 v[18:33], v[188:191], v[192:195], v[18:33]
	ds_write_b128 v76, v[54:57] offset:27648
	ds_write_b128 v70, v[46:49] offset:46080
	v_mfma_f32_32x32x16_bf16 v[2:17], v[196:199], v[192:195], v[2:17]
	ds_write_b128 v72, v[50:53] offset:46080
	s_setprio 0
	s_min_u32 s5, s4, 12
	s_lshl_b32 s14, s5, 7
	v_lshl_add_u64 v[34:35], v[58:59], 0, s[14:15]
	v_lshl_add_u64 v[38:39], v[60:61], 0, s[14:15]
	v_lshl_add_u64 v[42:43], v[62:63], 0, s[14:15]
	v_lshl_add_u64 v[46:47], v[64:65], 0, s[14:15]
	v_lshl_add_u64 v[48:49], v[66:67], 0, s[14:15]
	v_lshl_add_u64 v[50:51], v[68:69], 0, s[14:15]
	s_waitcnt lgkmcnt(0)
	s_barrier
	ds_read_b128 v[176:179], v0 offset:27648
	ds_read_b128 v[180:183], v71 offset:46080
	ds_read_b128 v[184:187], v0 offset:32256
	s_setprio 1
	ds_read_b128 v[188:191], v0 offset:27680
	ds_read_b128 v[192:195], v71 offset:46112
	ds_read_b128 v[196:199], v0 offset:32288
	s_waitcnt lgkmcnt(3)
	v_mfma_f32_32x32x16_bf16 v[18:33], v[176:179], v[180:183], v[18:33]
	v_mfma_f32_32x32x16_bf16 v[2:17], v[184:187], v[180:183], v[2:17]
	ds_read_b128 v[176:179], v0 offset:27712
	ds_read_b128 v[180:183], v71 offset:46144
	ds_read_b128 v[184:187], v0 offset:32320
	s_waitcnt lgkmcnt(3)
	v_mfma_f32_32x32x16_bf16 v[18:33], v[188:191], v[192:195], v[18:33]
	v_mfma_f32_32x32x16_bf16 v[2:17], v[196:199], v[192:195], v[2:17]
	ds_read_b128 v[188:191], v0 offset:27744
	ds_read_b128 v[192:195], v71 offset:46176
	ds_read_b128 v[196:199], v0 offset:32352
	s_waitcnt lgkmcnt(3)
	v_mfma_f32_32x32x16_bf16 v[18:33], v[176:179], v[180:183], v[18:33]
	v_mfma_f32_32x32x16_bf16 v[2:17], v[184:187], v[180:183], v[2:17]
	s_waitcnt lgkmcnt(0)
	v_mfma_f32_32x32x16_bf16 v[18:33], v[188:191], v[192:195], v[18:33]
	v_mfma_f32_32x32x16_bf16 v[2:17], v[196:199], v[192:195], v[2:17]
	s_setprio 0
	s_cmp_lt_u32 s4, 14
	s_waitcnt lgkmcnt(0)
	s_barrier
; #define TIDX (tid_launder())
; #define G_STORE(ST, S, unused) do { char* d_ = smem + (ST) * STAGE; \
;     *(uint4*)(d_ + alo[0]) = S##a0; *(uint4*)(d_ + alo[1]) = S##a1; *(uint4*)(d_ + alo[2]) = S##a2; *(uint4*)(d_ + alo[3]) = S##a3; \
;     *(uint4*)(d_ + blo[0]) = S##b0; *(uint4*)(d_ + blo[1]) = S##b1; \
;     if (NBCH == 4) { *(uint4*)(d_ + blo[NBCH - 2]) = S##b2; *(uint4*)(d_ + blo[NBCH - 1]) = S##b3; } } while (0)
; template <int NJ, class RowA>
; DI void gemm_main(f32x16 (&acc)[2][NJ], const bf16_t* __restrict__ A, RowA rowA, size_t kstrideA, int m0, int Mmax,
;                   const bf16_t* __restrict__ Bt, size_t ldb, int n0, int nk, char* smem) {
;     ...
;   const int tid = TIDX, lane = tid & 63, wid = tid >> 6, wm = wid >> 1, wn = wid & 1;
;   const int r = lane & 31, hh = lane >> 5;
;   const bf16_t* ap[4]; const bf16_t* bp[NBCH]; int alo[4], blo[NBCH];
; #pragma unroll
;   for (int i = 0; i < 4; ++i) {
;     const int c = tid + 256 * i, row = c >> 3, kc = c & 7;
;     int m = m0 + row; m = m < Mmax ? m : Mmax - 1;
;     ap[i] = A + rowA(m) + kc * 8; alo[i] = row * 144 + kc * 16;
;   }
; #pragma unroll
;   for (int i = 0; i < NBCH; ++i) {
;     const int c = tid + 256 * i, row = c >> 3, kc = c & 7;
;     bp[i] = Bt + (size_t)(n0 + row) * ldb + kc * 8; blo[i] = 128 * 144 + row * 144 + kc * 16;
;   }
; #pragma unroll
;   for (int i = 0; i < 2; ++i)
; #pragma unroll
;     for (int j = 0; j < NJ; ++j)
; #pragma unroll
;       for (int e = 0; e < 16; ++e) acc[i][j][e] = 0.f;
;   uint4 x0a0, x0a1, x0a2, x0a3, x0b0, x0b1, x0b2, x0b3, x1a0, x1a1, x1a2, x1a3, x1b0, x1b1, x1b2, x1b3;
;   x0b2 = x0b3 = x1b2 = x1b3 = make_uint4(0, 0, 0, 0);
;     ...
;   __syncthreads();
;   G_LOAD(x0, 0, 0);
;   G_LOAD(x1, 0, 1);
;   G_STORE(0, x0, 0);
;   __syncthreads();
; DI void merge_tile(const Params& p, int mt, int nt, char* smem) {
;     ...
;   for (int x = 0; x < 3; ++x) {
;     const int koff = x == 0 ? 0 : (x == 1 ? 256 : 768);
;     const int nkp = x == 1 ? 8 : 4;
;     f32x16 ag[2][1], ap[2][1];
;     gemm_main<1>(ag, p.h, RowLin{1024}, 64, m0, T_TOK, p.wt_in + (size_t)(4224 + x * 1024) * 1024, 1024, n0, 16, smem);
;     gemm_main<1>(ap, p.projZ + koff, RowLin{LDA_Z}, 64, m0, T_TOK, p.wt_br + koff, 1024, n0, nkp, smem);
	s_setprio 2
	s_cmp_eq_u32 s3, 1
	s_cselect_b32 s5, s42, 0x300
	s_cselect_b32 s4, 8, 4
	s_cmp_lg_u32 s3, 0
	v_mov_b32_e32 v58, v230
	s_cselect_b32 s5, s5, 0
	v_readlane_b32 s16, v252, 57
	s_lshl_b32 s5, s5, 1
	v_ashrrev_i32_e32 v59, 3, v58
	v_readlane_b32 s28, v253, 5
	s_waitcnt vmcnt(5)
	v_add_u32_e32 v36, s1, v59
	v_readlane_b32 s29, v253, 6
	s_add_u32 s6, s28, s5
	v_lshlrev_b32_e32 v0, 4, v58
	v_min_i32_e32 v36, 0x7fff, v36
	s_addc_u32 s7, s29, 0
	v_and_b32_e32 v0, 0x70, v0
	v_ashrrev_i32_e32 v37, 31, v36
	v_lshl_add_u64 v[34:35], s[6:7], 0, v[0:1]
	v_lshlrev_b64 v[36:37], 11, v[36:37]
	v_lshl_add_u64 v[122:123], v[34:35], 0, v[36:37]
	v_add_u32_e32 v36, 0x100, v58
	v_ashrrev_i32_e32 v60, 3, v36
	v_add_u32_e32 v36, s1, v60
	v_min_i32_e32 v36, 0x7fff, v36
	v_ashrrev_i32_e32 v37, 31, v36
	v_lshlrev_b64 v[36:37], 11, v[36:37]
	v_lshl_add_u64 v[124:125], v[34:35], 0, v[36:37]
	v_add_u32_e32 v36, 0x200, v58
	v_ashrrev_i32_e32 v61, 3, v36
	v_add_u32_e32 v36, s1, v61
	v_min_i32_e32 v36, 0x7fff, v36
	v_ashrrev_i32_e32 v37, 31, v36
	v_lshlrev_b64 v[36:37], 11, v[36:37]
	v_lshl_add_u64 v[126:127], v[34:35], 0, v[36:37]
	v_add_u32_e32 v36, 0x300, v58
	v_ashrrev_i32_e32 v62, 3, v36
	v_add_u32_e32 v36, s1, v62
	v_min_i32_e32 v36, 0x7fff, v36
	v_ashrrev_i32_e32 v37, 31, v36
	v_lshlrev_b64 v[36:37], 11, v[36:37]
	v_readlane_b32 s17, v252, 58
	s_add_u32 s8, s16, s5
	v_lshl_add_u64 v[128:129], v[34:35], 0, v[36:37]
	v_add_u32_e32 v36, s2, v59
	s_addc_u32 s9, s17, 0
	v_ashrrev_i32_e32 v37, 31, v36
	v_lshl_add_u64 v[34:35], s[8:9], 0, v[0:1]
	v_lshlrev_b64 v[36:37], 11, v[36:37]
	v_lshl_add_u64 v[130:131], v[34:35], 0, v[36:37]
	v_add_u32_e32 v36, s2, v60
	v_ashrrev_i32_e32 v37, 31, v36
	v_lshlrev_b64 v[36:37], 11, v[36:37]
	v_lshl_add_u64 v[132:133], v[34:35], 0, v[36:37]
	s_barrier
	global_load_dwordx4 v[34:37], v[122:123], off
	global_load_dwordx4 v[38:41], v[124:125], off
	global_load_dwordx4 v[42:45], v[126:127], off
	global_load_dwordx4 v[46:49], v[128:129], off
	global_load_dwordx4 v[50:53], v[130:131], off
	global_load_dwordx4 v[54:57], v[132:133], off
	global_load_dwordx4 v[66:69], v[122:123], off offset:128
	global_load_dwordx4 v[70:73], v[124:125], off offset:128
	global_load_dwordx4 v[74:77], v[126:127], off offset:128
	global_load_dwordx4 v[78:81], v[128:129], off offset:128
	global_load_dwordx4 v[82:85], v[130:131], off offset:128
	global_load_dwordx4 v[86:89], v[132:133], off offset:128
	v_and_b32_e32 v63, 31, v58
	v_lshrrev_b32_e32 v58, 1, v58
	v_and_or_b32 v64, v58, s47, v63
	v_and_b32_e32 v65, 16, v58
	v_and_or_b32 v58, v58, 32, v63
	v_mad_u64_u32 v[134:135], s[6:7], v59, s76, v[0:1]
	v_mad_u64_u32 v[136:137], s[6:7], v60, s76, v[0:1]
	v_mad_u64_u32 v[138:139], s[6:7], v61, s76, v[0:1]
	v_mad_u64_u32 v[140:141], s[6:7], v62, s76, v[0:1]
	v_mul_u32_u24_e32 v58, 0x90, v58
	v_mul_lo_u32 v0, v64, s76
	s_mov_b32 s5, 3
	s_add_i32 s6, s4, -1
	v_add_u32_e32 v0, v65, v0
	v_add_u32_e32 v135, v58, v65
	v_readlane_b32 s18, v252, 59
	v_readlane_b32 s19, v252, 60
	v_readlane_b32 s20, v252, 61
	v_readlane_b32 s21, v252, 62
	v_readlane_b32 s22, v252, 63
	v_readlane_b32 s23, v253, 0
	v_readlane_b32 s24, v253, 1
	v_readlane_b32 s25, v253, 2
	v_readlane_b32 s26, v253, 3
	v_readlane_b32 s27, v253, 4
	v_readlane_b32 s30, v253, 7
	v_readlane_b32 s31, v253, 8
	s_waitcnt vmcnt(11)
	ds_write_b128 v134, v[34:37]
	s_waitcnt vmcnt(10)
	ds_write_b128 v136, v[38:41]
	s_waitcnt vmcnt(9)
	ds_write_b128 v138, v[42:45]
	s_waitcnt vmcnt(8)
	ds_write_b128 v140, v[46:49]
	s_waitcnt vmcnt(7)
	ds_write_b128 v134, v[50:53] offset:18432
	s_waitcnt vmcnt(6)
	ds_write_b128 v136, v[54:57] offset:18432
	v_mov_b32_e32 v34, 0
	v_mov_b32_e32 v35, v34
	v_mov_b32_e32 v36, v34
	v_mov_b32_e32 v37, v34
	v_mov_b32_e32 v38, v34
	v_mov_b32_e32 v39, v34
	v_mov_b32_e32 v40, v34
	v_mov_b32_e32 v41, v34
	v_mov_b32_e32 v42, v34
	v_mov_b32_e32 v43, v34
	v_mov_b32_e32 v44, v34
	v_mov_b32_e32 v45, v34
	v_mov_b32_e32 v46, v34
	v_mov_b32_e32 v47, v34
	v_mov_b32_e32 v48, v34
	v_mov_b32_e32 v49, v34
	v_mov_b32_e32 v50, v34
	v_mov_b32_e32 v51, v34
	v_mov_b32_e32 v52, v34
	v_mov_b32_e32 v53, v34
	v_mov_b32_e32 v54, v34
	v_mov_b32_e32 v55, v34
	v_mov_b32_e32 v56, v34
	v_mov_b32_e32 v57, v34
	v_mov_b32_e32 v58, v34
	v_mov_b32_e32 v59, v34
	v_mov_b32_e32 v60, v34
	v_mov_b32_e32 v61, v34
	v_mov_b32_e32 v62, v34
	v_mov_b32_e32 v63, v34
	v_mov_b32_e32 v64, v34
	v_mov_b32_e32 v65, v34
	s_waitcnt lgkmcnt(0)
	s_barrier

; DI float sigmoidf(float x) { return __builtin_amdgcn_rcpf(1.f + __expf(-x)); }
; #define G_STORE(ST, S, unused) do { char* d_ = smem + (ST) * STAGE; \
;     *(uint4*)(d_ + alo[0]) = S##a0; *(uint4*)(d_ + alo[1]) = S##a1; *(uint4*)(d_ + alo[2]) = S##a2; *(uint4*)(d_ + alo[3]) = S##a3; \
;     *(uint4*)(d_ + blo[0]) = S##b0; *(uint4*)(d_ + blo[1]) = S##b1; \
;     if (NBCH == 4) { *(uint4*)(d_ + blo[NBCH - 2]) = S##b2; *(uint4*)(d_ + blo[NBCH - 1]) = S##b3; } } while (0)
; template <int NJ, class RowA>
; DI void gemm_main(f32x16 (&acc)[2][NJ], const bf16_t* __restrict__ A, RowA rowA, size_t kstrideA, int m0, int Mmax,
;                   const bf16_t* __restrict__ Bt, size_t ldb, int n0, int nk, char* smem) {
;     ...
;   __syncthreads();
;   G_LOAD(x0, 0, 0);
;   G_LOAD(x1, 0, 1);
;   G_STORE(0, x0, 0);
;   __syncthreads();
; #pragma unroll 1
;   for (int kt = 0; kt < nk; kt += 2) {
;     G_LOAD(x0, 0, (kt + 2 < nk ? kt + 2 : nk - 1));
;     G_COMPUTE(0);
;     G_STORE(1, x1, 0);
;     __syncthreads();
;     G_LOAD(x1, 0, (kt + 3 < nk ? kt + 3 : nk - 1));
;     G_COMPUTE(1);
;     G_STORE(0, x0, 0);
;     __syncthreads();
; DI void merge_tile(const Params& p, int mt, int nt, char* smem) {
;     ...
; #pragma unroll
;     for (int i = 0; i < 2; ++i)
; #pragma unroll
;       for (int e = 0; e < 16; ++e) mac[i][0][e] += sigmoidf(ag[i][0][e]) * ap[i][0][e];
.Lpeel_tail_21:
	ds_read_b128 v[176:179], v0
	ds_read_b128 v[180:183], v135 offset:18432
	ds_read_b128 v[184:187], v0 offset:4608
	s_add_i32 s7, s5, -1
	s_min_u32 s14, s7, s6
	s_lshl_b64 s[8:9], s[14:15], 7
	v_lshl_add_u64 v[144:145], v[122:123], 0, s[8:9]
	v_lshl_add_u64 v[148:149], v[124:125], 0, s[8:9]
	v_lshl_add_u64 v[152:153], v[126:127], 0, s[8:9]
	v_lshl_add_u64 v[156:157], v[128:129], 0, s[8:9]
	v_lshl_add_u64 v[160:161], v[130:131], 0, s[8:9]
	v_lshl_add_u64 v[164:165], v[132:133], 0, s[8:9]
	s_setprio 1
	ds_read_b128 v[188:191], v0 offset:32
	ds_read_b128 v[192:195], v135 offset:18464
	ds_read_b128 v[196:199], v0 offset:4640
	s_waitcnt lgkmcnt(3)
	v_mfma_f32_32x32x16_bf16 v[50:65], v[176:179], v[180:183], v[50:65]
	v_mfma_f32_32x32x16_bf16 v[34:49], v[184:187], v[180:183], v[34:49]
	ds_read_b128 v[176:179], v0 offset:64
	ds_read_b128 v[180:183], v135 offset:18496
	ds_read_b128 v[184:187], v0 offset:4672
	s_waitcnt lgkmcnt(3)
	v_mfma_f32_32x32x16_bf16 v[50:65], v[188:191], v[192:195], v[50:65]
	v_mfma_f32_32x32x16_bf16 v[34:49], v[196:199], v[192:195], v[34:49]
	ds_read_b128 v[188:191], v0 offset:96
	ds_read_b128 v[192:195], v135 offset:18528
	ds_read_b128 v[196:199], v0 offset:4704
	s_waitcnt lgkmcnt(3)
	v_mfma_f32_32x32x16_bf16 v[50:65], v[176:179], v[180:183], v[50:65]
	s_waitcnt vmcnt(0)
	ds_write_b128 v134, v[66:69] offset:27648
	ds_write_b128 v136, v[70:73] offset:27648
	v_mfma_f32_32x32x16_bf16 v[34:49], v[184:187], v[180:183], v[34:49]
	ds_write_b128 v138, v[74:77] offset:27648
	s_waitcnt lgkmcnt(3)
	v_mfma_f32_32x32x16_bf16 v[50:65], v[188:191], v[192:195], v[50:65]
	ds_write_b128 v140, v[78:81] offset:27648
	ds_write_b128 v134, v[82:85] offset:46080
	v_mfma_f32_32x32x16_bf16 v[34:49], v[196:199], v[192:195], v[34:49]
	ds_write_b128 v136, v[86:89] offset:46080
	s_setprio 0
	s_min_u32 s14, s5, s6
	s_lshl_b64 s[8:9], s[14:15], 7
	v_lshl_add_u64 v[66:67], v[122:123], 0, s[8:9]
	v_lshl_add_u64 v[70:71], v[124:125], 0, s[8:9]
	v_lshl_add_u64 v[74:75], v[126:127], 0, s[8:9]
	v_lshl_add_u64 v[78:79], v[128:129], 0, s[8:9]
	v_lshl_add_u64 v[82:83], v[130:131], 0, s[8:9]
	v_lshl_add_u64 v[86:87], v[132:133], 0, s[8:9]
	s_waitcnt lgkmcnt(0)
	s_barrier
	ds_read_b128 v[176:179], v0 offset:27648
	ds_read_b128 v[180:183], v135 offset:46080
	ds_read_b128 v[184:187], v0 offset:32256
	s_setprio 1
	ds_read_b128 v[188:191], v0 offset:27680
	ds_read_b128 v[192:195], v135 offset:46112
	ds_read_b128 v[196:199], v0 offset:32288
	s_waitcnt lgkmcnt(3)
	v_mfma_f32_32x32x16_bf16 v[50:65], v[176:179], v[180:183], v[50:65]
	v_mfma_f32_32x32x16_bf16 v[34:49], v[184:187], v[180:183], v[34:49]
	ds_read_b128 v[176:179], v0 offset:27712
	ds_read_b128 v[180:183], v135 offset:46144
	ds_read_b128 v[184:187], v0 offset:32320
	s_waitcnt lgkmcnt(3)
	v_mfma_f32_32x32x16_bf16 v[50:65], v[188:191], v[192:195], v[50:65]
	v_mfma_f32_32x32x16_bf16 v[34:49], v[196:199], v[192:195], v[34:49]
	ds_read_b128 v[188:191], v0 offset:27744
	ds_read_b128 v[192:195], v135 offset:46176
	ds_read_b128 v[196:199], v0 offset:32352
	s_waitcnt lgkmcnt(3)
	v_mfma_f32_32x32x16_bf16 v[50:65], v[176:179], v[180:183], v[50:65]
	v_mfma_f32_32x32x16_bf16 v[34:49], v[184:187], v[180:183], v[34:49]
	s_waitcnt lgkmcnt(0)
	v_mfma_f32_32x32x16_bf16 v[50:65], v[188:191], v[192:195], v[50:65]
	v_mfma_f32_32x32x16_bf16 v[34:49], v[196:199], v[192:195], v[34:49]
	s_setprio 0
	s_add_i32 s5, s5, 2
	s_cmp_lt_u32 s7, s4
	s_waitcnt lgkmcnt(0)
	s_barrier
	s_setprio 2
	v_mul_f32_e32 v0, 0xbfb8aa3b, v18
	v_exp_f32_e32 v0, v0
	v_mul_f32_e32 v18, 0xbfb8aa3b, v19
	v_exp_f32_e32 v18, v18
	s_add_i32 s3, s3, 1
	v_add_f32_e32 v0, 1.0, v0
	s_cmp_lg_u32 s3, 3
	v_add_f32_e32 v19, 1.0, v18
	v_rcp_f32_e32 v18, v0
	v_mul_f32_e32 v0, 0xbfb8aa3b, v20
	v_exp_f32_e32 v0, v0
	v_mul_f32_e32 v20, 0xbfb8aa3b, v21
	v_rcp_f32_e32 v19, v19
	v_exp_f32_e32 v20, v20
	v_add_f32_e32 v0, 1.0, v0
	v_pk_fma_f32 v[120:121], v[18:19], v[50:51], v[120:121]
	v_rcp_f32_e32 v18, v0
	v_add_f32_e32 v0, 1.0, v20
	v_rcp_f32_e32 v19, v0
	v_mul_f32_e32 v0, 0xbfb8aa3b, v22
	v_exp_f32_e32 v0, v0
	v_mul_f32_e32 v20, 0xbfb8aa3b, v23
	v_exp_f32_e32 v20, v20
	v_pk_fma_f32 v[118:119], v[18:19], v[52:53], v[118:119]
	v_add_f32_e32 v0, 1.0, v0
	v_rcp_f32_e32 v18, v0
	v_add_f32_e32 v0, 1.0, v20
	v_rcp_f32_e32 v19, v0
	v_mul_f32_e32 v0, 0xbfb8aa3b, v24
	v_exp_f32_e32 v0, v0
	v_mul_f32_e32 v20, 0xbfb8aa3b, v25
	v_exp_f32_e32 v20, v20
	v_pk_fma_f32 v[116:117], v[18:19], v[54:55], v[116:117]
	v_add_f32_e32 v0, 1.0, v0
	v_rcp_f32_e32 v18, v0
	v_add_f32_e32 v0, 1.0, v20
	v_rcp_f32_e32 v19, v0
	v_mul_f32_e32 v0, 0xbfb8aa3b, v26
	v_exp_f32_e32 v0, v0
	v_mul_f32_e32 v20, 0xbfb8aa3b, v27
	v_exp_f32_e32 v20, v20
	v_pk_fma_f32 v[114:115], v[18:19], v[56:57], v[114:115]
	v_add_f32_e32 v0, 1.0, v0
	v_rcp_f32_e32 v18, v0
	v_add_f32_e32 v0, 1.0, v20
	v_rcp_f32_e32 v19, v0
	v_mul_f32_e32 v0, 0xbfb8aa3b, v28
	v_exp_f32_e32 v0, v0
	v_mul_f32_e32 v20, 0xbfb8aa3b, v29
	v_exp_f32_e32 v20, v20
	v_pk_fma_f32 v[112:113], v[18:19], v[58:59], v[112:113]
	v_add_f32_e32 v0, 1.0, v0
	v_rcp_f32_e32 v18, v0
	v_add_f32_e32 v0, 1.0, v20
	v_rcp_f32_e32 v19, v0
	v_mul_f32_e32 v0, 0xbfb8aa3b, v30
	v_exp_f32_e32 v0, v0
	v_mul_f32_e32 v20, 0xbfb8aa3b, v31
	v_exp_f32_e32 v20, v20
	v_pk_fma_f32 v[110:111], v[18:19], v[60:61], v[110:111]
	v_add_f32_e32 v0, 1.0, v0
	v_rcp_f32_e32 v18, v0
	v_add_f32_e32 v0, 1.0, v20
	v_rcp_f32_e32 v19, v0
	v_mul_f32_e32 v0, 0xbfb8aa3b, v32
	v_exp_f32_e32 v0, v0
	v_mul_f32_e32 v20, 0xbfb8aa3b, v33
	v_exp_f32_e32 v20, v20
	v_pk_fma_f32 v[108:109], v[18:19], v[62:63], v[108:109]
	v_add_f32_e32 v0, 1.0, v0
	v_rcp_f32_e32 v18, v0
	v_add_f32_e32 v0, 1.0, v20
	v_rcp_f32_e32 v19, v0
; DI float sigmoidf(float x) { return __builtin_amdgcn_rcpf(1.f + __expf(-x)); }
; DI void merge_tile(const Params& p, int mt, int nt, char* smem) {
;     ...
; #pragma unroll
;     for (int i = 0; i < 2; ++i)
; #pragma unroll
;       for (int e = 0; e < 16; ++e) mac[i][0][e] += sigmoidf(ag[i][0][e]) * ap[i][0][e];
;   }
;   float* Ct = (float*)smem;
;   acc_to_ct<1>(mac, Ct);
	v_mul_f32_e32 v0, 0xbfb8aa3b, v2
	v_exp_f32_e32 v0, v0
	v_mul_f32_e32 v2, 0xbfb8aa3b, v3
	v_exp_f32_e32 v3, v2
	v_pk_fma_f32 v[106:107], v[18:19], v[64:65], v[106:107]
	v_add_f32_e32 v0, 1.0, v0
	v_rcp_f32_e32 v2, v0
	v_add_f32_e32 v0, 1.0, v3
	v_rcp_f32_e32 v3, v0
	v_mul_f32_e32 v0, 0xbfb8aa3b, v4
	v_exp_f32_e32 v0, v0
	v_mul_f32_e32 v4, 0xbfb8aa3b, v5
	v_exp_f32_e32 v4, v4
	v_pk_fma_f32 v[104:105], v[2:3], v[34:35], v[104:105]
	v_add_f32_e32 v0, 1.0, v0
	v_rcp_f32_e32 v2, v0
	v_add_f32_e32 v0, 1.0, v4
	v_rcp_f32_e32 v3, v0
	v_mul_f32_e32 v0, 0xbfb8aa3b, v6
	v_exp_f32_e32 v0, v0
	v_mul_f32_e32 v4, 0xbfb8aa3b, v7
	v_exp_f32_e32 v4, v4
	v_pk_fma_f32 v[102:103], v[2:3], v[36:37], v[102:103]
	v_add_f32_e32 v0, 1.0, v0
	v_rcp_f32_e32 v2, v0
	v_add_f32_e32 v0, 1.0, v4
	v_rcp_f32_e32 v3, v0
	v_mul_f32_e32 v0, 0xbfb8aa3b, v8
	v_exp_f32_e32 v0, v0
	v_mul_f32_e32 v4, 0xbfb8aa3b, v9
	v_exp_f32_e32 v4, v4
	v_pk_fma_f32 v[100:101], v[2:3], v[38:39], v[100:101]
	v_add_f32_e32 v0, 1.0, v0
	v_rcp_f32_e32 v2, v0
	v_add_f32_e32 v0, 1.0, v4
	v_rcp_f32_e32 v3, v0
	v_mul_f32_e32 v0, 0xbfb8aa3b, v10
	v_exp_f32_e32 v0, v0
	v_mul_f32_e32 v4, 0xbfb8aa3b, v11
	v_exp_f32_e32 v4, v4
	v_pk_fma_f32 v[98:99], v[2:3], v[40:41], v[98:99]
	v_add_f32_e32 v0, 1.0, v0
	v_rcp_f32_e32 v2, v0
	v_add_f32_e32 v0, 1.0, v4
	v_rcp_f32_e32 v3, v0
	v_mul_f32_e32 v0, 0xbfb8aa3b, v12
	v_exp_f32_e32 v0, v0
	v_mul_f32_e32 v4, 0xbfb8aa3b, v13
	v_exp_f32_e32 v4, v4
	v_pk_fma_f32 v[96:97], v[2:3], v[42:43], v[96:97]
	v_add_f32_e32 v0, 1.0, v0
	v_rcp_f32_e32 v2, v0
	v_add_f32_e32 v0, 1.0, v4
	v_rcp_f32_e32 v3, v0
	v_mul_f32_e32 v0, 0xbfb8aa3b, v14
	v_exp_f32_e32 v0, v0
	v_mul_f32_e32 v4, 0xbfb8aa3b, v15
	v_exp_f32_e32 v4, v4
	v_pk_fma_f32 v[94:95], v[2:3], v[44:45], v[94:95]
	v_add_f32_e32 v0, 1.0, v0
	v_mul_f32_e32 v3, 0xbfb8aa3b, v16
	v_rcp_f32_e32 v2, v0
	v_add_f32_e32 v0, 1.0, v4
	v_exp_f32_e32 v4, v3
	v_mul_f32_e32 v3, 0xbfb8aa3b, v17
	v_exp_f32_e32 v5, v3
	v_rcp_f32_e32 v3, v0
	v_add_f32_e32 v0, 1.0, v4
	v_rcp_f32_e32 v4, v0
	v_add_f32_e32 v0, 1.0, v5
	v_rcp_f32_e32 v5, v0
	v_pk_fma_f32 v[92:93], v[2:3], v[46:47], v[92:93]
	v_pk_fma_f32 v[90:91], v[4:5], v[48:49], v[90:91]
	s_cbranch_scc1 .LBB0_18
	v_mov_b32_e32 v0, v230
	v_mov_b32_e32 v2, v230
	v_and_b32_e32 v3, 31, v0
	v_lshrrev_b32_e32 v0, 3, v0
	v_and_b32_e32 v0, 4, v0
	v_lshrrev_b32_e32 v4, 1, v2
	v_and_or_b32 v4, v4, s47, v0
	v_lshlrev_b32_e32 v0, 1, v2
	v_and_b32_e32 v0, 0x80, v0
	v_lshl_or_b32 v0, v3, 2, v0
	v_mad_u64_u32 v[2:3], s[4:5], v4, s79, v[0:1]
	v_add_u32_e32 v0, 0x400, v2
	ds_write2_b32 v0, v118, v119 offset0:8 offset1:140
	v_add_u32_e32 v0, 0x1000, v2
	ds_write2_b32 v0, v116, v117 offset0:32 offset1:164
	v_add_u32_e32 v0, 0x1400, v2
	ds_write2_b32 v0, v114, v115 offset0:40 offset1:172
	v_add_u32_e32 v0, 0x2000, v2
	ds_write2_b32 v0, v112, v113 offset0:64 offset1:196
	v_add_u32_e32 v0, 0x2400, v2
	ds_write2_b32 v0, v110, v111 offset0:72 offset1:204
	v_add_u32_e32 v0, 0x3000, v2
	ds_write2_b32 v0, v108, v109 offset0:96 offset1:228
	v_add_u32_e32 v0, 0x3400, v2
	ds_write2_b32 v0, v106, v107 offset0:104 offset1:236
	v_add_u32_e32 v0, 0x4200, v2
	ds_write2_b32 v0, v104, v105 offset1:132
	v_add_u32_e32 v0, 0x4600, v2
	ds_write2_b32 v0, v102, v103 offset0:8 offset1:140
	v_add_u32_e32 v0, 0x5200, v2
	ds_write2_b32 v0, v100, v101 offset0:32 offset1:164
	v_add_u32_e32 v0, 0x5600, v2
	ds_write2_b32 v0, v98, v99 offset0:40 offset1:172
	v_add_u32_e32 v0, 0x6200, v2
	ds_write2_b32 v0, v96, v97 offset0:64 offset1:196
	v_add_u32_e32 v0, 0x6600, v2
	ds_write2_b32 v0, v94, v95 offset0:72 offset1:204
	v_add_u32_e32 v0, 0x7200, v2
	ds_write2_b32 v0, v92, v93 offset0:96 offset1:228
	v_add_u32_e32 v0, 0x7600, v2
	ds_write2_b32 v0, v90, v91 offset0:104 offset1:236
	v_mov_b32_e32 v0, v230
	ds_write2_b32 v2, v120, v121 offset1:132
	s_waitcnt lgkmcnt(0)
	s_barrier
; DI unsigned pack2(float a, float b) { hwf2 v = {a, b}; hwbf2 r = __builtin_convertvector(v, hwbf2); return __builtin_bit_cast(unsigned, r); }
; DI float siluf(float x) { return x * __builtin_amdgcn_rcpf(1.f + __expf(-x)); }
; DI void epi_store64(const float* Ct, int cb, const float* rn, int grp, const float* gain, bool silu, const float* bias,
;                     bf16_t* dst, size_t ldd, int dcol0, int m0, int Mmax) {
;     ...
;   for (int q = 0; q < 8; ++q) {
;     const int row = (tid >> 4) + 16 * q;
;     float4 v = *(const float4*)(Ct + row * 132 + cb + c);
;     v.x += bv.x; v.y += bv.y; v.z += bv.z; v.w += bv.w;
;     if (rn) { const float sc = rn[row * 2 + grp]; v.x *= sc * gv.x; v.y *= sc * gv.y; v.z *= sc * gv.z; v.w *= sc * gv.w; }
;     if (silu) { v.x = siluf(v.x); v.y = siluf(v.y); v.z = siluf(v.z); v.w = siluf(v.w); }
;     uint2 o; o.x = pack2(v.x, v.y); o.y = pack2(v.z, v.w);
;     *(uint2*)(dst + (size_t)(m0 + row) * ldd + dcol0 + c) = o;
;   }
; __global__ void __launch_bounds__(256, 2) mega(Params p, int ph_lo, int ph_hi) {
;     ...
;         for (int idx = blockIdx.x >> 3; idx < 512; idx += gridDim.x >> 3) { const int t = (blockIdx.x & 7) * 512 + idx; merge_tile(p, t >> 4, t & 15, smem); }
	s_lshl_b32 s2, s2, 1
	v_lshlrev_b32_e32 v2, 2, v0
	v_ashrrev_i32_e32 v12, 4, v0
	v_and_b32_e32 v6, 60, v2
	v_mul_lo_u32 v0, v12, s79
	v_lshl_add_u32 v14, v6, 2, v0
	ds_read_b128 v[2:5], v14
	v_readlane_b32 s4, v250, 50
	v_lshlrev_b32_e32 v0, 1, v6
	ds_read_b128 v[6:9], v14 offset:8448
	v_readlane_b32 s5, v250, 51
	s_add_u32 s2, s4, s2
	v_add_u32_e32 v12, s1, v12
	s_addc_u32 s3, s5, 0
	s_waitcnt lgkmcnt(1)
	v_pk_add_f32 v[2:3], v[2:3], 0 op_sel_hi:[1,0]
	v_pk_add_f32 v[4:5], v[4:5], 0 op_sel_hi:[1,0]
	v_ashrrev_i32_e32 v13, 31, v12
	v_lshl_add_u64 v[10:11], s[2:3], 0, v[0:1]
	v_cvt_pk_bf16_f32 v2, v2, v3
	v_cvt_pk_bf16_f32 v3, v4, v5
	v_lshlrev_b64 v[4:5], 11, v[12:13]
	v_lshl_add_u64 v[4:5], v[10:11], 0, v[4:5]
	global_store_dwordx2 v[4:5], v[2:3], off
	s_waitcnt lgkmcnt(0)
	v_pk_add_f32 v[2:3], v[6:7], 0 op_sel_hi:[1,0]
	v_pk_add_f32 v[4:5], v[8:9], 0 op_sel_hi:[1,0]
	v_cvt_pk_bf16_f32 v6, v2, v3
	v_cvt_pk_bf16_f32 v7, v4, v5
	ds_read_b128 v[2:5], v14 offset:16896
	v_add_u32_e32 v8, 16, v12
	v_ashrrev_i32_e32 v9, 31, v8
	v_lshlrev_b64 v[8:9], 11, v[8:9]
	v_lshl_add_u64 v[8:9], v[10:11], 0, v[8:9]
	global_store_dwordx2 v[8:9], v[6:7], off
	ds_read_b128 v[6:9], v14 offset:25344
	s_waitcnt lgkmcnt(1)
	v_pk_add_f32 v[2:3], v[2:3], 0 op_sel_hi:[1,0]
	v_pk_add_f32 v[4:5], v[4:5], 0 op_sel_hi:[1,0]
	v_cvt_pk_bf16_f32 v2, v2, v3
	v_cvt_pk_bf16_f32 v3, v4, v5
	v_add_u32_e32 v4, 32, v12
	v_ashrrev_i32_e32 v5, 31, v4
	v_lshlrev_b64 v[4:5], 11, v[4:5]
	v_lshl_add_u64 v[4:5], v[10:11], 0, v[4:5]
	global_store_dwordx2 v[4:5], v[2:3], off
	s_waitcnt lgkmcnt(0)
	v_pk_add_f32 v[2:3], v[6:7], 0 op_sel_hi:[1,0]
	v_pk_add_f32 v[4:5], v[8:9], 0 op_sel_hi:[1,0]
	v_cvt_pk_bf16_f32 v6, v2, v3
	v_cvt_pk_bf16_f32 v7, v4, v5
	ds_read_b128 v[2:5], v14 offset:33792
	v_add_u32_e32 v8, 48, v12
	v_ashrrev_i32_e32 v9, 31, v8
	v_lshlrev_b64 v[8:9], 11, v[8:9]
	v_lshl_add_u64 v[8:9], v[10:11], 0, v[8:9]
	global_store_dwordx2 v[8:9], v[6:7], off
	ds_read_b128 v[6:9], v14 offset:42240
	s_waitcnt lgkmcnt(1)
	v_pk_add_f32 v[2:3], v[2:3], 0 op_sel_hi:[1,0]
	v_pk_add_f32 v[4:5], v[4:5], 0 op_sel_hi:[1,0]
	v_cvt_pk_bf16_f32 v2, v2, v3
	v_cvt_pk_bf16_f32 v3, v4, v5
	v_add_u32_e32 v4, 64, v12
	v_ashrrev_i32_e32 v5, 31, v4
	v_lshlrev_b64 v[4:5], 11, v[4:5]
	v_lshl_add_u64 v[4:5], v[10:11], 0, v[4:5]
	global_store_dwordx2 v[4:5], v[2:3], off
	s_waitcnt lgkmcnt(0)
	v_pk_add_f32 v[2:3], v[6:7], 0 op_sel_hi:[1,0]
	v_pk_add_f32 v[4:5], v[8:9], 0 op_sel_hi:[1,0]
	v_cvt_pk_bf16_f32 v6, v2, v3
	v_cvt_pk_bf16_f32 v7, v4, v5
	ds_read_b128 v[2:5], v14 offset:50688
	v_add_u32_e32 v8, 0x50, v12
	v_ashrrev_i32_e32 v9, 31, v8
	v_lshlrev_b64 v[8:9], 11, v[8:9]
	v_lshl_add_u64 v[8:9], v[10:11], 0, v[8:9]
	global_store_dwordx2 v[8:9], v[6:7], off
	ds_read_b128 v[6:9], v14 offset:59136
	s_waitcnt lgkmcnt(1)
	v_pk_add_f32 v[2:3], v[2:3], 0 op_sel_hi:[1,0]
	v_pk_add_f32 v[4:5], v[4:5], 0 op_sel_hi:[1,0]
	v_cvt_pk_bf16_f32 v2, v2, v3
	v_cvt_pk_bf16_f32 v3, v4, v5
	v_add_u32_e32 v4, 0x60, v12
	v_ashrrev_i32_e32 v5, 31, v4
	v_lshlrev_b64 v[4:5], 11, v[4:5]
	v_lshl_add_u64 v[4:5], v[10:11], 0, v[4:5]
	global_store_dwordx2 v[4:5], v[2:3], off
	s_waitcnt lgkmcnt(0)
	v_pk_add_f32 v[2:3], v[6:7], 0 op_sel_hi:[1,0]
	v_pk_add_f32 v[4:5], v[8:9], 0 op_sel_hi:[1,0]
	v_cvt_pk_bf16_f32 v2, v2, v3
	v_cvt_pk_bf16_f32 v3, v4, v5
	v_add_u32_e32 v4, 0x70, v12
	v_ashrrev_i32_e32 v5, 31, v4
	v_readlane_b32 s1, v250, 60
	v_lshlrev_b64 v[4:5], 11, v[4:5]
	s_add_i32 s0, s0, s1
	v_lshl_add_u64 v[4:5], v[10:11], 0, v[4:5]
	s_cmpk_gt_u32 s0, 0x1ff
	v_readlane_b32 s6, v250, 52
	v_readlane_b32 s7, v250, 53
	global_store_dwordx2 v[4:5], v[2:3], off
	s_barrier
	s_cbranch_scc0 .LBB0_17

; #define G_STORE(ST, S, unused) do { char* d_ = smem + (ST) * STAGE; \
;     *(uint4*)(d_ + alo[0]) = S##a0; *(uint4*)(d_ + alo[1]) = S##a1; *(uint4*)(d_ + alo[2]) = S##a2; *(uint4*)(d_ + alo[3]) = S##a3; \
;     *(uint4*)(d_ + blo[0]) = S##b0; *(uint4*)(d_ + blo[1]) = S##b1; \
;     if (NBCH == 4) { *(uint4*)(d_ + blo[NBCH - 2]) = S##b2; *(uint4*)(d_ + blo[NBCH - 1]) = S##b3; } } while (0)
; template <int NJ, class RowA>
; DI void gemm_main(f32x16 (&acc)[2][NJ], const bf16_t* __restrict__ A, RowA rowA, size_t kstrideA, int m0, int Mmax,
;                   const bf16_t* __restrict__ Bt, size_t ldb, int n0, int nk, char* smem) {
;     ...
;   __syncthreads();
;   G_LOAD(x0, 0, 0);
;   G_LOAD(x1, 0, 1);
;   G_STORE(0, x0, 0);
;   __syncthreads();
; #pragma unroll 1
;   for (int kt = 0; kt < nk; kt += 2) {
;     G_LOAD(x0, 0, (kt + 2 < nk ? kt + 2 : nk - 1));
;     G_COMPUTE(0);
;     G_STORE(1, x1, 0);
;     __syncthreads();
;     G_LOAD(x1, 0, (kt + 3 < nk ? kt + 3 : nk - 1));
;     G_COMPUTE(1);
;     G_STORE(0, x0, 0);
;     __syncthreads();
.Lpeel_tail_1956:
	ds_read_b128 v[166:169], v0
	ds_read_b128 v[170:173], v139 offset:18432
	ds_read_b128 v[174:177], v139 offset:23040
	ds_read_b128 v[178:181], v0 offset:4608
	s_add_i32 s1, s0, 4
	s_min_u32 s1, s1, 15
	s_lshl_b32 s14, s1, 7
	v_lshl_add_u64 v[98:99], v[122:123], 0, s[14:15]
	v_lshl_add_u64 v[102:103], v[124:125], 0, s[14:15]
	v_lshl_add_u64 v[106:107], v[126:127], 0, s[14:15]
	v_lshl_add_u64 v[110:111], v[128:129], 0, s[14:15]
	v_lshl_add_u64 v[114:115], v[130:131], 0, s[14:15]
	v_lshl_add_u64 v[118:119], v[132:133], 0, s[14:15]
	s_add_i32 s0, s0, 2
	v_lshl_add_u64 v[158:159], v[134:135], 0, s[14:15]
	v_lshl_add_u64 v[160:161], v[136:137], 0, s[14:15]
	s_setprio 1
	ds_read_b128 v[182:185], v0 offset:32
	ds_read_b128 v[186:189], v139 offset:18464
	ds_read_b128 v[190:193], v139 offset:23072
	ds_read_b128 v[194:197], v0 offset:4640
	s_waitcnt lgkmcnt(4)
	v_mfma_f32_32x32x16_bf16 v[50:65], v[166:169], v[170:173], v[50:65]
	v_mfma_f32_32x32x16_bf16 v[34:49], v[166:169], v[174:177], v[34:49]
	v_mfma_f32_32x32x16_bf16 v[18:33], v[178:181], v[170:173], v[18:33]
	v_mfma_f32_32x32x16_bf16 v[2:17], v[178:181], v[174:177], v[2:17]
	ds_read_b128 v[166:169], v0 offset:64
	ds_read_b128 v[170:173], v139 offset:18496
	ds_read_b128 v[174:177], v139 offset:23104
	ds_read_b128 v[178:181], v0 offset:4672
	s_waitcnt lgkmcnt(4)
	v_mfma_f32_32x32x16_bf16 v[50:65], v[182:185], v[186:189], v[50:65]
	v_mfma_f32_32x32x16_bf16 v[34:49], v[182:185], v[190:193], v[34:49]
	v_mfma_f32_32x32x16_bf16 v[18:33], v[194:197], v[186:189], v[18:33]
	v_mfma_f32_32x32x16_bf16 v[2:17], v[194:197], v[190:193], v[2:17]
	ds_read_b128 v[182:185], v0 offset:96
	ds_read_b128 v[186:189], v139 offset:18528
	ds_read_b128 v[190:193], v139 offset:23136
	ds_read_b128 v[194:197], v0 offset:4704
	s_waitcnt lgkmcnt(4)
	v_mfma_f32_32x32x16_bf16 v[50:65], v[166:169], v[170:173], v[50:65]
	s_waitcnt vmcnt(0)
	ds_write_b128 v138, v[74:77] offset:36864
	v_mfma_f32_32x32x16_bf16 v[34:49], v[166:169], v[174:177], v[34:49]
	ds_write_b128 v140, v[78:81] offset:36864
	v_mfma_f32_32x32x16_bf16 v[18:33], v[178:181], v[170:173], v[18:33]
	ds_write_b128 v142, v[82:85] offset:36864
	v_mfma_f32_32x32x16_bf16 v[2:17], v[178:181], v[174:177], v[2:17]
	ds_write_b128 v144, v[86:89] offset:36864
	s_waitcnt lgkmcnt(4)
	v_mfma_f32_32x32x16_bf16 v[50:65], v[182:185], v[186:189], v[50:65]
	ds_write_b128 v138, v[90:93] offset:55296
	v_mfma_f32_32x32x16_bf16 v[34:49], v[182:185], v[190:193], v[34:49]
	ds_write_b128 v140, v[94:97] offset:55296
	v_mfma_f32_32x32x16_bf16 v[18:33], v[194:197], v[186:189], v[18:33]
	ds_write_b128 v142, v[66:69] offset:55296
	v_mfma_f32_32x32x16_bf16 v[2:17], v[194:197], v[190:193], v[2:17]
	ds_write_b128 v144, v[70:73] offset:55296
	s_setprio 0
	s_min_u32 s1, s0, 12
	s_lshl_b32 s14, s1, 7
	v_lshl_add_u64 v[66:67], v[122:123], 0, s[14:15]
	v_lshl_add_u64 v[68:69], v[124:125], 0, s[14:15]
	v_lshl_add_u64 v[70:71], v[126:127], 0, s[14:15]
	v_lshl_add_u64 v[72:73], v[128:129], 0, s[14:15]
	v_lshl_add_u64 v[90:91], v[130:131], 0, s[14:15]
	v_lshl_add_u64 v[94:95], v[132:133], 0, s[14:15]
	s_waitcnt lgkmcnt(0)
	s_barrier
	ds_read_b128 v[166:169], v0 offset:36864
	ds_read_b128 v[170:173], v139 offset:55296
	ds_read_b128 v[174:177], v139 offset:59904
	ds_read_b128 v[178:181], v0 offset:41472
	v_lshl_add_u64 v[154:155], v[134:135], 0, s[14:15]
	v_lshl_add_u64 v[156:157], v[136:137], 0, s[14:15]
	s_setprio 1
	ds_read_b128 v[182:185], v0 offset:36896
	ds_read_b128 v[186:189], v139 offset:55328
	ds_read_b128 v[190:193], v139 offset:59936
	ds_read_b128 v[194:197], v0 offset:41504
	s_waitcnt lgkmcnt(4)
	v_mfma_f32_32x32x16_bf16 v[50:65], v[166:169], v[170:173], v[50:65]
	v_mfma_f32_32x32x16_bf16 v[34:49], v[166:169], v[174:177], v[34:49]
	v_mfma_f32_32x32x16_bf16 v[18:33], v[178:181], v[170:173], v[18:33]
	v_mfma_f32_32x32x16_bf16 v[2:17], v[178:181], v[174:177], v[2:17]
	ds_read_b128 v[166:169], v0 offset:36928
	ds_read_b128 v[170:173], v139 offset:55360
	ds_read_b128 v[174:177], v139 offset:59968
	ds_read_b128 v[178:181], v0 offset:41536
	s_waitcnt lgkmcnt(4)
	v_mfma_f32_32x32x16_bf16 v[50:65], v[182:185], v[186:189], v[50:65]
	v_mfma_f32_32x32x16_bf16 v[34:49], v[182:185], v[190:193], v[34:49]
	v_mfma_f32_32x32x16_bf16 v[18:33], v[194:197], v[186:189], v[18:33]
	v_mfma_f32_32x32x16_bf16 v[2:17], v[194:197], v[190:193], v[2:17]
	ds_read_b128 v[182:185], v0 offset:36960
	ds_read_b128 v[186:189], v139 offset:55392
	ds_read_b128 v[190:193], v139 offset:60000
	ds_read_b128 v[194:197], v0 offset:41568
	s_waitcnt lgkmcnt(4)
	v_mfma_f32_32x32x16_bf16 v[50:65], v[166:169], v[170:173], v[50:65]
	v_mfma_f32_32x32x16_bf16 v[34:49], v[166:169], v[174:177], v[34:49]
	v_mfma_f32_32x32x16_bf16 v[18:33], v[178:181], v[170:173], v[18:33]
	v_mfma_f32_32x32x16_bf16 v[2:17], v[178:181], v[174:177], v[2:17]
	s_waitcnt lgkmcnt(0)
	v_mfma_f32_32x32x16_bf16 v[50:65], v[182:185], v[186:189], v[50:65]
	v_mfma_f32_32x32x16_bf16 v[34:49], v[182:185], v[190:193], v[34:49]
	v_mfma_f32_32x32x16_bf16 v[18:33], v[194:197], v[186:189], v[18:33]
	v_mfma_f32_32x32x16_bf16 v[2:17], v[194:197], v[190:193], v[2:17]
	s_setprio 0
	s_cmp_lt_u32 s0, 14
	s_waitcnt lgkmcnt(0)
	s_barrier
; #define TIDX (tid_launder())
; DI int crow(int reg, int hh) { return (reg & 3) + 8 * (reg >> 2) + 4 * hh; }
; template <int NJ>
; DI void acc_to_ct(const f32x16 (&acc)[2][NJ], float* Ct) {
;   const int lane = TIDX & 63, wid = TIDX >> 6, wm = wid >> 1, wn = wid & 1;
;   const int r = lane & 31, hh = lane >> 5;
; #pragma unroll
;   for (int i = 0; i < 2; ++i)
; #pragma unroll
;     for (int j = 0; j < NJ; ++j)
; #pragma unroll
;       for (int e = 0; e < 16; ++e) Ct[(wm * 64 + i * 32 + crow(e, hh)) * 132 + wn * 32 * NJ + j * 32 + r] = acc[i][j][e];
;   __syncthreads();
; DI void inproj_tile(const Params& p, int l, int mt, int tn, char* smem) {
;     ...
;   } else if (tn <= 24) {
;     const int c0 = (tn - 13) * 128;
;     epi_store64(Ct, 0, nullptr, 0, nullptr, false, nullptr, p.projB, LDA_B, c0, m0, T_TOK);
;     epi_store64(Ct, 64, nullptr, 0, nullptr, false, nullptr, p.projB, LDA_B, c0 + 64, m0, T_TOK);
;   } else {
;     const int c0 = (tn - 25) * 128;
;     epi_store64(Ct, 0, nullptr, 0, nullptr, true, nullptr, p.projZ, LDA_Z, c0, m0, T_TOK);
;     epi_store64(Ct, 64, nullptr, 0, nullptr, true, nullptr, p.projZ, LDA_Z, c0 + 64, m0, T_TOK);
	s_setprio 2
	v_mov_b32_e32 v0, v230
	s_waitcnt vmcnt(1)
	v_mov_b32_e32 v66, v230
	v_and_b32_e32 v67, 31, v0
	v_lshrrev_b32_e32 v0, 3, v0
	v_and_b32_e32 v0, 4, v0
	v_lshrrev_b32_e32 v68, 1, v66
	v_and_or_b32 v0, v68, s47, v0
	v_and_or_b32 v66, v66, 64, v67
	v_mul_lo_u32 v0, v0, s79
	v_lshl_add_u32 v0, v66, 2, v0
	ds_write2_b32 v0, v50, v34 offset1:32
	ds_write2_b32 v0, v51, v35 offset0:132 offset1:164
	v_add_u32_e32 v34, 0x400, v0
	ds_write2_b32 v34, v52, v36 offset0:8 offset1:40
	ds_write2_b32 v34, v53, v37 offset0:140 offset1:172
	v_add_u32_e32 v34, 0x1000, v0
	ds_write2_b32 v34, v54, v38 offset0:32 offset1:64
	ds_write2_b32 v34, v55, v39 offset0:164 offset1:196
	v_add_u32_e32 v34, 0x1400, v0
	ds_write2_b32 v34, v56, v40 offset0:40 offset1:72
	ds_write2_b32 v34, v57, v41 offset0:172 offset1:204
	v_add_u32_e32 v34, 0x2000, v0
	ds_write2_b32 v34, v58, v42 offset0:64 offset1:96
	ds_write2_b32 v34, v59, v43 offset0:196 offset1:228
	v_add_u32_e32 v34, 0x2400, v0
	ds_write2_b32 v34, v60, v44 offset0:72 offset1:104
	ds_write2_b32 v34, v61, v45 offset0:204 offset1:236
	v_add_u32_e32 v34, 0x3000, v0
	ds_write2_b32 v34, v62, v46 offset0:96 offset1:128
	v_add_u32_e32 v34, 0x3200, v0
	ds_write2_b32 v34, v63, v47 offset0:100 offset1:132
	v_add_u32_e32 v34, 0x3400, v0
	ds_write2_b32 v34, v64, v48 offset0:104 offset1:136
	v_add_u32_e32 v34, 0x3600, v0
	ds_write2_b32 v34, v65, v49 offset0:108 offset1:140
	v_add_u32_e32 v34, 0x4000, v0
	ds_write2_b32 v34, v18, v2 offset0:128 offset1:160
	v_add_u32_e32 v2, 0x4400, v0
	ds_write2_b32 v2, v19, v3 offset0:4 offset1:36
	ds_write2_b32 v2, v20, v4 offset0:136 offset1:168
	v_add_u32_e32 v2, 0x4800, v0
	ds_write2_b32 v2, v21, v5 offset0:12 offset1:44
	v_add_u32_e32 v2, 0x5000, v0
	ds_write2_b32 v2, v22, v6 offset0:160 offset1:192
	v_add_u32_e32 v2, 0x5400, v0
	ds_write2_b32 v2, v23, v7 offset0:36 offset1:68
	ds_write2_b32 v2, v24, v8 offset0:168 offset1:200
	v_add_u32_e32 v2, 0x5800, v0
	ds_write2_b32 v2, v25, v9 offset0:44 offset1:76
	v_add_u32_e32 v2, 0x6000, v0
	ds_write2_b32 v2, v26, v10 offset0:192 offset1:224
	v_add_u32_e32 v2, 0x6400, v0
	ds_write2_b32 v2, v27, v11 offset0:68 offset1:100
	ds_write2_b32 v2, v28, v12 offset0:200 offset1:232
	v_add_u32_e32 v2, 0x6800, v0
	ds_write2_b32 v2, v29, v13 offset0:76 offset1:108
	v_add_u32_e32 v2, 0x7200, v0
	ds_write2_b32 v2, v30, v14 offset0:96 offset1:128
	v_add_u32_e32 v2, 0x7400, v0
	ds_write2_b32 v2, v31, v15 offset0:100 offset1:132
	v_add_u32_e32 v2, 0x7600, v0
	v_add_u32_e32 v0, 0x7800, v0
	s_cmp_gt_i32 s12, 3
	s_mov_b64 s[0:1], -1
	ds_write2_b32 v2, v32, v16 offset0:104 offset1:136
	ds_write2_b32 v0, v33, v17 offset0:108 offset1:140
	s_waitcnt lgkmcnt(0)
	s_barrier
	s_cbranch_scc0 .LBB0_2086
	s_cmp_lg_u32 s12, 4
	s_cbranch_scc0 .LBB0_2045
	s_cmp_gt_u32 s12, 8
	s_cbranch_scc0 .LBB0_2042
	s_ashr_i32 s0, s3, 7
	s_add_i32 s4, s0, s4
	s_ashr_i32 s0, s11, 31
	s_lshr_b32 s0, s0, 21
	s_add_i32 s0, s11, s0
	s_and_b32 s0, s0, 0xfffff800
	s_sub_i32 s13, s11, s0
	s_cmp_lt_i32 s12, 11
	s_mov_b64 s[0:1], -1
	s_cbranch_scc1 .LBB0_2012
	s_cmp_lt_i32 s12, 12
	s_cbranch_scc1 .LBB0_1982
	s_cmp_lg_u32 s12, 12
	s_cbranch_scc0 .LBB0_1968
	s_cmp_gt_u32 s12, 24
	s_mov_b32 s3, s15
	s_cbranch_scc0 .LBB0_1965
	v_mov_b32_e32 v0, v230
	v_readlane_b32 s16, v252, 57
	s_lshl_b64 s[0:1], s[2:3], 1
	v_lshlrev_b32_e32 v2, 2, v0
	v_readlane_b32 s28, v253, 5
	v_and_b32_e32 v4, 60, v2
	v_readlane_b32 s29, v253, 6
	s_add_u32 s0, s28, s0
	v_ashrrev_i32_e32 v10, 4, v0
	s_addc_u32 s1, s29, s1
	v_lshlrev_b32_e32 v0, 1, v4
	v_lshl_add_u64 v[2:3], s[0:1], 0, v[0:1]
	v_mul_lo_u32 v0, v10, s79
	v_lshl_add_u32 v0, v4, 2, v0
	ds_read_b128 v[4:7], v0
	s_movk_i32 s6, 0xe700
	s_mov_b32 s7, -1
	v_lshl_add_u64 v[2:3], v[2:3], 0, s[6:7]
	v_readlane_b32 s17, v252, 58
	s_waitcnt lgkmcnt(0)
	v_pk_add_f32 v[4:5], v[4:5], 0 op_sel_hi:[1,0]
	v_pk_add_f32 v[6:7], v[6:7], 0 op_sel_hi:[1,0]
	v_mul_f32_e32 v8, 0xbfb8aa3b, v4
	v_mul_f32_e32 v9, 0xbfb8aa3b, v5
	v_exp_f32_e32 v8, v8
	v_exp_f32_e32 v9, v9
	v_readlane_b32 s18, v252, 59
	v_readlane_b32 s19, v252, 60
	v_add_f32_e32 v8, 1.0, v8
	v_add_f32_e32 v9, 1.0, v9
	v_rcp_f32_e32 v8, v8
	v_rcp_f32_e32 v9, v9
	v_readlane_b32 s20, v252, 61
	v_readlane_b32 s21, v252, 62
	v_readlane_b32 s22, v252, 63
	v_pk_mul_f32 v[4:5], v[4:5], v[8:9]
	v_mul_f32_e32 v8, 0xbfb8aa3b, v6
	v_mul_f32_e32 v9, 0xbfb8aa3b, v7
	v_exp_f32_e32 v8, v8
	v_exp_f32_e32 v9, v9
	v_readlane_b32 s23, v253, 0
	v_readlane_b32 s24, v253, 1
	v_add_f32_e32 v8, 1.0, v8
	v_add_f32_e32 v9, 1.0, v9
	v_rcp_f32_e32 v8, v8
	v_rcp_f32_e32 v9, v9
	v_readlane_b32 s25, v253, 2
	v_readlane_b32 s26, v253, 3
	v_readlane_b32 s27, v253, 4
	v_pk_mul_f32 v[6:7], v[6:7], v[8:9]
	v_cvt_pk_bf16_f32 v8, v4, v5
	v_add_u32_e32 v4, s11, v10
	v_ashrrev_i32_e32 v5, 31, v4
	v_cvt_pk_bf16_f32 v9, v6, v7
	v_lshlrev_b64 v[6:7], 11, v[4:5]
	v_lshl_add_u64 v[6:7], v[2:3], 0, v[6:7]
	global_store_dwordx2 v[6:7], v[8:9], off
	ds_read_b128 v[6:9], v0 offset:8448
	v_readlane_b32 s30, v253, 7
	v_readlane_b32 s31, v253, 8
	s_waitcnt lgkmcnt(0)
	v_pk_add_f32 v[6:7], v[6:7], 0 op_sel_hi:[1,0]
	s_nop 0
	v_mul_f32_e32 v5, 0xbfb8aa3b, v6
	v_exp_f32_e32 v5, v5
	v_pk_add_f32 v[8:9], v[8:9], 0 op_sel_hi:[1,0]
	v_add_f32_e32 v5, 1.0, v5
	v_rcp_f32_e32 v10, v5
	v_mul_f32_e32 v5, 0xbfb8aa3b, v7
	v_exp_f32_e32 v5, v5
	s_nop 0
	v_add_f32_e32 v5, 1.0, v5
	v_rcp_f32_e32 v11, v5
	v_mul_f32_e32 v5, 0xbfb8aa3b, v8
	v_exp_f32_e32 v5, v5
	v_pk_mul_f32 v[6:7], v[6:7], v[10:11]
	s_nop 0
	v_cvt_pk_bf16_f32 v6, v6, v7
	v_add_f32_e32 v5, 1.0, v5
	v_rcp_f32_e32 v10, v5
	v_mul_f32_e32 v5, 0xbfb8aa3b, v9
	v_exp_f32_e32 v5, v5
	s_nop 0
	v_add_f32_e32 v5, 1.0, v5
	v_rcp_f32_e32 v11, v5
	s_nop 0
	v_pk_mul_f32 v[8:9], v[8:9], v[10:11]
	s_nop 0
	v_cvt_pk_bf16_f32 v7, v8, v9
	v_add_u32_e32 v8, 16, v4
	v_ashrrev_i32_e32 v9, 31, v8
	v_lshlrev_b64 v[8:9], 11, v[8:9]
	v_lshl_add_u64 v[8:9], v[2:3], 0, v[8:9]
	global_store_dwordx2 v[8:9], v[6:7], off
	ds_read_b128 v[6:9], v0 offset:16896
	s_waitcnt lgkmcnt(0)
; DI unsigned pack2(float a, float b) { hwf2 v = {a, b}; hwbf2 r = __builtin_convertvector(v, hwbf2); return __builtin_bit_cast(unsigned, r); }
; DI float siluf(float x) { return x * __builtin_amdgcn_rcpf(1.f + __expf(-x)); }
; DI void epi_store64(const float* Ct, int cb, const float* rn, int grp, const float* gain, bool silu, const float* bias,
;                     bf16_t* dst, size_t ldd, int dcol0, int m0, int Mmax) {
;     ...
;   for (int q = 0; q < 8; ++q) {
;     const int row = (tid >> 4) + 16 * q;
;     float4 v = *(const float4*)(Ct + row * 132 + cb + c);
;     v.x += bv.x; v.y += bv.y; v.z += bv.z; v.w += bv.w;
;     if (rn) { const float sc = rn[row * 2 + grp]; v.x *= sc * gv.x; v.y *= sc * gv.y; v.z *= sc * gv.z; v.w *= sc * gv.w; }
;     if (silu) { v.x = siluf(v.x); v.y = siluf(v.y); v.z = siluf(v.z); v.w = siluf(v.w); }
;     uint2 o; o.x = pack2(v.x, v.y); o.y = pack2(v.z, v.w);
;     *(uint2*)(dst + (size_t)(m0 + row) * ldd + dcol0 + c) = o;
;   }
	v_pk_add_f32 v[6:7], v[6:7], 0 op_sel_hi:[1,0]
	s_nop 0
	v_mul_f32_e32 v5, 0xbfb8aa3b, v6
	v_exp_f32_e32 v5, v5
	v_pk_add_f32 v[8:9], v[8:9], 0 op_sel_hi:[1,0]
	v_add_f32_e32 v5, 1.0, v5
	v_rcp_f32_e32 v10, v5
	v_mul_f32_e32 v5, 0xbfb8aa3b, v7
	v_exp_f32_e32 v5, v5
	s_nop 0
	v_add_f32_e32 v5, 1.0, v5
	v_rcp_f32_e32 v11, v5
	v_mul_f32_e32 v5, 0xbfb8aa3b, v8
	v_exp_f32_e32 v5, v5
	v_pk_mul_f32 v[6:7], v[6:7], v[10:11]
	s_nop 0
	v_cvt_pk_bf16_f32 v6, v6, v7
	v_add_f32_e32 v5, 1.0, v5
	v_rcp_f32_e32 v10, v5
	v_mul_f32_e32 v5, 0xbfb8aa3b, v9
	v_exp_f32_e32 v5, v5
	s_nop 0
	v_add_f32_e32 v5, 1.0, v5
	v_rcp_f32_e32 v11, v5
	s_nop 0
	v_pk_mul_f32 v[8:9], v[8:9], v[10:11]
	s_nop 0
	v_cvt_pk_bf16_f32 v7, v8, v9
	v_add_u32_e32 v8, 32, v4
	v_ashrrev_i32_e32 v9, 31, v8
	v_lshlrev_b64 v[8:9], 11, v[8:9]
	v_lshl_add_u64 v[8:9], v[2:3], 0, v[8:9]
	global_store_dwordx2 v[8:9], v[6:7], off
	ds_read_b128 v[6:9], v0 offset:25344
	s_waitcnt lgkmcnt(0)
	v_pk_add_f32 v[6:7], v[6:7], 0 op_sel_hi:[1,0]
	s_nop 0
	v_mul_f32_e32 v5, 0xbfb8aa3b, v6
	v_exp_f32_e32 v5, v5
	v_pk_add_f32 v[8:9], v[8:9], 0 op_sel_hi:[1,0]
	v_add_f32_e32 v5, 1.0, v5
	v_rcp_f32_e32 v10, v5
	v_mul_f32_e32 v5, 0xbfb8aa3b, v7
	v_exp_f32_e32 v5, v5
	s_nop 0
	v_add_f32_e32 v5, 1.0, v5
	v_rcp_f32_e32 v11, v5
	v_mul_f32_e32 v5, 0xbfb8aa3b, v8
	v_exp_f32_e32 v5, v5
	v_pk_mul_f32 v[6:7], v[6:7], v[10:11]
	s_nop 0
	v_cvt_pk_bf16_f32 v6, v6, v7
	v_add_f32_e32 v5, 1.0, v5
	v_rcp_f32_e32 v10, v5
	v_mul_f32_e32 v5, 0xbfb8aa3b, v9
	v_exp_f32_e32 v5, v5
	s_nop 0
	v_add_f32_e32 v5, 1.0, v5
	v_rcp_f32_e32 v11, v5
	s_nop 0
	v_pk_mul_f32 v[8:9], v[8:9], v[10:11]
	s_nop 0
	v_cvt_pk_bf16_f32 v7, v8, v9
	v_add_u32_e32 v8, 48, v4
	v_ashrrev_i32_e32 v9, 31, v8
	v_lshlrev_b64 v[8:9], 11, v[8:9]
	v_lshl_add_u64 v[8:9], v[2:3], 0, v[8:9]
	global_store_dwordx2 v[8:9], v[6:7], off
	ds_read_b128 v[6:9], v0 offset:33792
	s_waitcnt lgkmcnt(0)
	v_pk_add_f32 v[6:7], v[6:7], 0 op_sel_hi:[1,0]
	s_nop 0
	v_mul_f32_e32 v5, 0xbfb8aa3b, v6
	v_exp_f32_e32 v5, v5
	v_pk_add_f32 v[8:9], v[8:9], 0 op_sel_hi:[1,0]
	v_add_f32_e32 v5, 1.0, v5
	v_rcp_f32_e32 v10, v5
	v_mul_f32_e32 v5, 0xbfb8aa3b, v7
	v_exp_f32_e32 v5, v5
	s_nop 0
	v_add_f32_e32 v5, 1.0, v5
	v_rcp_f32_e32 v11, v5
	v_mul_f32_e32 v5, 0xbfb8aa3b, v8
	v_exp_f32_e32 v5, v5
	v_pk_mul_f32 v[6:7], v[6:7], v[10:11]
	s_nop 0
	v_cvt_pk_bf16_f32 v6, v6, v7
	v_add_f32_e32 v5, 1.0, v5
	v_rcp_f32_e32 v10, v5
	v_mul_f32_e32 v5, 0xbfb8aa3b, v9
	v_exp_f32_e32 v5, v5
	s_nop 0
	v_add_f32_e32 v5, 1.0, v5
	v_rcp_f32_e32 v11, v5
	s_nop 0
	v_pk_mul_f32 v[8:9], v[8:9], v[10:11]
	s_nop 0
	v_cvt_pk_bf16_f32 v7, v8, v9
	v_add_u32_e32 v8, 64, v4
	v_ashrrev_i32_e32 v9, 31, v8
	v_lshlrev_b64 v[8:9], 11, v[8:9]
	v_lshl_add_u64 v[8:9], v[2:3], 0, v[8:9]
	global_store_dwordx2 v[8:9], v[6:7], off
	ds_read_b128 v[6:9], v0 offset:42240
	s_waitcnt lgkmcnt(0)
	v_pk_add_f32 v[6:7], v[6:7], 0 op_sel_hi:[1,0]
	s_nop 0
	v_mul_f32_e32 v5, 0xbfb8aa3b, v6
	v_exp_f32_e32 v5, v5
	v_pk_add_f32 v[8:9], v[8:9], 0 op_sel_hi:[1,0]
	v_add_f32_e32 v5, 1.0, v5
	v_rcp_f32_e32 v10, v5
	v_mul_f32_e32 v5, 0xbfb8aa3b, v7
	v_exp_f32_e32 v5, v5
	s_nop 0
	v_add_f32_e32 v5, 1.0, v5
	v_rcp_f32_e32 v11, v5
	v_mul_f32_e32 v5, 0xbfb8aa3b, v8
	v_exp_f32_e32 v5, v5
	v_pk_mul_f32 v[6:7], v[6:7], v[10:11]
	s_nop 0
	v_cvt_pk_bf16_f32 v6, v6, v7
	v_add_f32_e32 v5, 1.0, v5
	v_rcp_f32_e32 v10, v5
	v_mul_f32_e32 v5, 0xbfb8aa3b, v9
	v_exp_f32_e32 v5, v5
	s_nop 0
	v_add_f32_e32 v5, 1.0, v5
	v_rcp_f32_e32 v11, v5
	s_nop 0
	v_pk_mul_f32 v[8:9], v[8:9], v[10:11]
	s_nop 0
	v_cvt_pk_bf16_f32 v7, v8, v9
	v_add_u32_e32 v8, 0x50, v4
	v_ashrrev_i32_e32 v9, 31, v8
	v_lshlrev_b64 v[8:9], 11, v[8:9]
	v_lshl_add_u64 v[8:9], v[2:3], 0, v[8:9]
	global_store_dwordx2 v[8:9], v[6:7], off
	ds_read_b128 v[6:9], v0 offset:50688
	s_waitcnt lgkmcnt(0)
	v_pk_add_f32 v[6:7], v[6:7], 0 op_sel_hi:[1,0]
	s_nop 0
	v_mul_f32_e32 v5, 0xbfb8aa3b, v6
	v_exp_f32_e32 v5, v5
	v_pk_add_f32 v[8:9], v[8:9], 0 op_sel_hi:[1,0]
	v_add_f32_e32 v5, 1.0, v5
	v_rcp_f32_e32 v10, v5
	v_mul_f32_e32 v5, 0xbfb8aa3b, v7
	v_exp_f32_e32 v5, v5
	s_nop 0
	v_add_f32_e32 v5, 1.0, v5
	v_rcp_f32_e32 v11, v5
	v_mul_f32_e32 v5, 0xbfb8aa3b, v8
	v_exp_f32_e32 v5, v5
	v_pk_mul_f32 v[6:7], v[6:7], v[10:11]
	s_nop 0
	v_cvt_pk_bf16_f32 v6, v6, v7
	v_add_f32_e32 v5, 1.0, v5
	v_rcp_f32_e32 v10, v5
	v_mul_f32_e32 v5, 0xbfb8aa3b, v9
	v_exp_f32_e32 v5, v5
	s_nop 0
	v_add_f32_e32 v5, 1.0, v5
	v_rcp_f32_e32 v11, v5
	s_nop 0
	v_pk_mul_f32 v[8:9], v[8:9], v[10:11]
	s_nop 0
	v_cvt_pk_bf16_f32 v7, v8, v9
	v_add_u32_e32 v8, 0x60, v4
	v_ashrrev_i32_e32 v9, 31, v8
	v_lshlrev_b64 v[8:9], 11, v[8:9]
	v_lshl_add_u64 v[8:9], v[2:3], 0, v[8:9]
	global_store_dwordx2 v[8:9], v[6:7], off
	ds_read_b128 v[6:9], v0 offset:59136
	v_add_u32_e32 v4, 0x70, v4
	v_ashrrev_i32_e32 v5, 31, v4
	v_lshlrev_b64 v[4:5], 11, v[4:5]
	v_lshl_add_u64 v[2:3], v[2:3], 0, v[4:5]
	s_waitcnt lgkmcnt(0)
	v_pk_add_f32 v[6:7], v[6:7], 0 op_sel_hi:[1,0]
	v_pk_add_f32 v[8:9], v[8:9], 0 op_sel_hi:[1,0]
	v_mul_f32_e32 v0, 0xbfb8aa3b, v6
	v_exp_f32_e32 v0, v0
	s_nop 0
	v_add_f32_e32 v0, 1.0, v0
	v_rcp_f32_e32 v10, v0
	v_mul_f32_e32 v0, 0xbfb8aa3b, v7
	v_exp_f32_e32 v0, v0
	s_nop 0
	v_add_f32_e32 v0, 1.0, v0
	v_rcp_f32_e32 v11, v0
	v_mul_f32_e32 v0, 0xbfb8aa3b, v8
	v_exp_f32_e32 v0, v0
	v_pk_mul_f32 v[6:7], v[6:7], v[10:11]
	s_nop 0
	v_cvt_pk_bf16_f32 v6, v6, v7
	v_add_f32_e32 v0, 1.0, v0
	v_rcp_f32_e32 v10, v0
	v_mul_f32_e32 v0, 0xbfb8aa3b, v9
	v_exp_f32_e32 v0, v0
	s_nop 0
	v_add_f32_e32 v0, 1.0, v0
	v_rcp_f32_e32 v11, v0
	v_mov_b32_e32 v0, v230
	v_pk_mul_f32 v[8:9], v[8:9], v[10:11]
	s_nop 0
	v_cvt_pk_bf16_f32 v7, v8, v9
	global_store_dwordx2 v[2:3], v[6:7], off
	s_nop 0
	v_lshlrev_b32_e32 v2, 2, v0
	v_and_b32_e32 v4, 60, v2
	v_ashrrev_i32_e32 v10, 4, v0
	v_lshlrev_b32_e32 v0, 1, v4
	v_lshl_add_u64 v[2:3], s[0:1], 0, v[0:1]
	v_mul_lo_u32 v0, v10, s79
	v_lshl_add_u32 v0, v4, 2, v0
	ds_read_b128 v[4:7], v0 offset:256
	s_movk_i32 s0, 0xe780
	s_mov_b32 s1, -1
	v_lshl_add_u64 v[2:3], v[2:3], 0, s[0:1]
	s_mov_b64 s[0:1], 0
	s_waitcnt lgkmcnt(0)
; DI unsigned pack2(float a, float b) { hwf2 v = {a, b}; hwbf2 r = __builtin_convertvector(v, hwbf2); return __builtin_bit_cast(unsigned, r); }
; DI float siluf(float x) { return x * __builtin_amdgcn_rcpf(1.f + __expf(-x)); }
; DI void epi_store64(const float* Ct, int cb, const float* rn, int grp, const float* gain, bool silu, const float* bias,
;                     bf16_t* dst, size_t ldd, int dcol0, int m0, int Mmax) {
;     ...
;   for (int q = 0; q < 8; ++q) {
;     const int row = (tid >> 4) + 16 * q;
;     float4 v = *(const float4*)(Ct + row * 132 + cb + c);
;     v.x += bv.x; v.y += bv.y; v.z += bv.z; v.w += bv.w;
;     if (rn) { const float sc = rn[row * 2 + grp]; v.x *= sc * gv.x; v.y *= sc * gv.y; v.z *= sc * gv.z; v.w *= sc * gv.w; }
;     if (silu) { v.x = siluf(v.x); v.y = siluf(v.y); v.z = siluf(v.z); v.w = siluf(v.w); }
;     uint2 o; o.x = pack2(v.x, v.y); o.y = pack2(v.z, v.w);
;     *(uint2*)(dst + (size_t)(m0 + row) * ldd + dcol0 + c) = o;
;   }
	v_pk_add_f32 v[4:5], v[4:5], 0 op_sel_hi:[1,0]
	v_pk_add_f32 v[6:7], v[6:7], 0 op_sel_hi:[1,0]
	v_mul_f32_e32 v8, 0xbfb8aa3b, v4
	v_mul_f32_e32 v9, 0xbfb8aa3b, v5
	v_exp_f32_e32 v8, v8
	v_exp_f32_e32 v9, v9
	v_add_f32_e32 v8, 1.0, v8
	v_add_f32_e32 v9, 1.0, v9
	v_rcp_f32_e32 v8, v8
	v_rcp_f32_e32 v9, v9
	s_nop 0
	v_pk_mul_f32 v[4:5], v[4:5], v[8:9]
	v_mul_f32_e32 v8, 0xbfb8aa3b, v6
	v_mul_f32_e32 v9, 0xbfb8aa3b, v7
	v_exp_f32_e32 v8, v8
	v_exp_f32_e32 v9, v9
	v_add_f32_e32 v8, 1.0, v8
	v_add_f32_e32 v9, 1.0, v9
	v_rcp_f32_e32 v8, v8
	v_rcp_f32_e32 v9, v9
	s_nop 0
	v_pk_mul_f32 v[6:7], v[6:7], v[8:9]
	v_cvt_pk_bf16_f32 v8, v4, v5
	v_add_u32_e32 v4, s11, v10
	v_ashrrev_i32_e32 v5, 31, v4
	v_cvt_pk_bf16_f32 v9, v6, v7
	v_lshlrev_b64 v[6:7], 11, v[4:5]
	v_lshl_add_u64 v[6:7], v[2:3], 0, v[6:7]
	global_store_dwordx2 v[6:7], v[8:9], off
	ds_read_b128 v[6:9], v0 offset:8704
	s_waitcnt lgkmcnt(0)
	v_pk_add_f32 v[6:7], v[6:7], 0 op_sel_hi:[1,0]
	s_nop 0
	v_mul_f32_e32 v5, 0xbfb8aa3b, v6
	v_exp_f32_e32 v5, v5
	v_pk_add_f32 v[8:9], v[8:9], 0 op_sel_hi:[1,0]
	v_add_f32_e32 v5, 1.0, v5
	v_rcp_f32_e32 v10, v5
	v_mul_f32_e32 v5, 0xbfb8aa3b, v7
	v_exp_f32_e32 v5, v5
	s_nop 0
	v_add_f32_e32 v5, 1.0, v5
	v_rcp_f32_e32 v11, v5
	v_mul_f32_e32 v5, 0xbfb8aa3b, v8
	v_exp_f32_e32 v5, v5
	v_pk_mul_f32 v[6:7], v[6:7], v[10:11]
	s_nop 0
	v_cvt_pk_bf16_f32 v6, v6, v7
	v_add_f32_e32 v5, 1.0, v5
	v_rcp_f32_e32 v10, v5
	v_mul_f32_e32 v5, 0xbfb8aa3b, v9
	v_exp_f32_e32 v5, v5
	s_nop 0
	v_add_f32_e32 v5, 1.0, v5
	v_rcp_f32_e32 v11, v5
	s_nop 0
	v_pk_mul_f32 v[8:9], v[8:9], v[10:11]
	s_nop 0
	v_cvt_pk_bf16_f32 v7, v8, v9
	v_add_u32_e32 v8, 16, v4
	v_ashrrev_i32_e32 v9, 31, v8
	v_lshlrev_b64 v[8:9], 11, v[8:9]
	v_lshl_add_u64 v[8:9], v[2:3], 0, v[8:9]
	global_store_dwordx2 v[8:9], v[6:7], off
	ds_read_b128 v[6:9], v0 offset:17152
	s_waitcnt lgkmcnt(0)
	v_pk_add_f32 v[6:7], v[6:7], 0 op_sel_hi:[1,0]
	s_nop 0
	v_mul_f32_e32 v5, 0xbfb8aa3b, v6
	v_exp_f32_e32 v5, v5
	v_pk_add_f32 v[8:9], v[8:9], 0 op_sel_hi:[1,0]
	v_add_f32_e32 v5, 1.0, v5
	v_rcp_f32_e32 v10, v5
	v_mul_f32_e32 v5, 0xbfb8aa3b, v7
	v_exp_f32_e32 v5, v5
	s_nop 0
	v_add_f32_e32 v5, 1.0, v5
	v_rcp_f32_e32 v11, v5
	v_mul_f32_e32 v5, 0xbfb8aa3b, v8
	v_exp_f32_e32 v5, v5
	v_pk_mul_f32 v[6:7], v[6:7], v[10:11]
	s_nop 0
	v_cvt_pk_bf16_f32 v6, v6, v7
	v_add_f32_e32 v5, 1.0, v5
	v_rcp_f32_e32 v10, v5
	v_mul_f32_e32 v5, 0xbfb8aa3b, v9
	v_exp_f32_e32 v5, v5
	s_nop 0
	v_add_f32_e32 v5, 1.0, v5
	v_rcp_f32_e32 v11, v5
	s_nop 0
	v_pk_mul_f32 v[8:9], v[8:9], v[10:11]
	s_nop 0
	v_cvt_pk_bf16_f32 v7, v8, v9
	v_add_u32_e32 v8, 32, v4
	v_ashrrev_i32_e32 v9, 31, v8
	v_lshlrev_b64 v[8:9], 11, v[8:9]
	v_lshl_add_u64 v[8:9], v[2:3], 0, v[8:9]
	global_store_dwordx2 v[8:9], v[6:7], off
	ds_read_b128 v[6:9], v0 offset:25600
	s_waitcnt lgkmcnt(0)
	v_pk_add_f32 v[6:7], v[6:7], 0 op_sel_hi:[1,0]
	s_nop 0
	v_mul_f32_e32 v5, 0xbfb8aa3b, v6
	v_exp_f32_e32 v5, v5
	v_pk_add_f32 v[8:9], v[8:9], 0 op_sel_hi:[1,0]
	v_add_f32_e32 v5, 1.0, v5
	v_rcp_f32_e32 v10, v5
	v_mul_f32_e32 v5, 0xbfb8aa3b, v7
	v_exp_f32_e32 v5, v5
	s_nop 0
	v_add_f32_e32 v5, 1.0, v5
	v_rcp_f32_e32 v11, v5
	v_mul_f32_e32 v5, 0xbfb8aa3b, v8
	v_exp_f32_e32 v5, v5
	v_pk_mul_f32 v[6:7], v[6:7], v[10:11]
	s_nop 0
	v_cvt_pk_bf16_f32 v6, v6, v7
	v_add_f32_e32 v5, 1.0, v5
	v_rcp_f32_e32 v10, v5
	v_mul_f32_e32 v5, 0xbfb8aa3b, v9
	v_exp_f32_e32 v5, v5
	s_nop 0
	v_add_f32_e32 v5, 1.0, v5
	v_rcp_f32_e32 v11, v5
	s_nop 0
	v_pk_mul_f32 v[8:9], v[8:9], v[10:11]
	s_nop 0
	v_cvt_pk_bf16_f32 v7, v8, v9
	v_add_u32_e32 v8, 48, v4
	v_ashrrev_i32_e32 v9, 31, v8
	v_lshlrev_b64 v[8:9], 11, v[8:9]
	v_lshl_add_u64 v[8:9], v[2:3], 0, v[8:9]
	global_store_dwordx2 v[8:9], v[6:7], off
	ds_read_b128 v[6:9], v0 offset:34048
	s_waitcnt lgkmcnt(0)
; DI unsigned pack2(float a, float b) { hwf2 v = {a, b}; hwbf2 r = __builtin_convertvector(v, hwbf2); return __builtin_bit_cast(unsigned, r); }
; DI float siluf(float x) { return x * __builtin_amdgcn_rcpf(1.f + __expf(-x)); }
; DI void epi_store64(const float* Ct, int cb, const float* rn, int grp, const float* gain, bool silu, const float* bias,
;                     bf16_t* dst, size_t ldd, int dcol0, int m0, int Mmax) {
;     ...
;   for (int q = 0; q < 8; ++q) {
;     const int row = (tid >> 4) + 16 * q;
;     float4 v = *(const float4*)(Ct + row * 132 + cb + c);
;     v.x += bv.x; v.y += bv.y; v.z += bv.z; v.w += bv.w;
;     if (rn) { const float sc = rn[row * 2 + grp]; v.x *= sc * gv.x; v.y *= sc * gv.y; v.z *= sc * gv.z; v.w *= sc * gv.w; }
;     if (silu) { v.x = siluf(v.x); v.y = siluf(v.y); v.z = siluf(v.z); v.w = siluf(v.w); }
;     uint2 o; o.x = pack2(v.x, v.y); o.y = pack2(v.z, v.w);
;     *(uint2*)(dst + (size_t)(m0 + row) * ldd + dcol0 + c) = o;
;   }
	v_pk_add_f32 v[6:7], v[6:7], 0 op_sel_hi:[1,0]
	s_nop 0
	v_mul_f32_e32 v5, 0xbfb8aa3b, v6
	v_exp_f32_e32 v5, v5
	v_pk_add_f32 v[8:9], v[8:9], 0 op_sel_hi:[1,0]
	v_add_f32_e32 v5, 1.0, v5
	v_rcp_f32_e32 v10, v5
	v_mul_f32_e32 v5, 0xbfb8aa3b, v7
	v_exp_f32_e32 v5, v5
	s_nop 0
	v_add_f32_e32 v5, 1.0, v5
	v_rcp_f32_e32 v11, v5
	v_mul_f32_e32 v5, 0xbfb8aa3b, v8
	v_exp_f32_e32 v5, v5
	v_pk_mul_f32 v[6:7], v[6:7], v[10:11]
	s_nop 0
	v_cvt_pk_bf16_f32 v6, v6, v7
	v_add_f32_e32 v5, 1.0, v5
	v_rcp_f32_e32 v10, v5
	v_mul_f32_e32 v5, 0xbfb8aa3b, v9
	v_exp_f32_e32 v5, v5
	s_nop 0
	v_add_f32_e32 v5, 1.0, v5
	v_rcp_f32_e32 v11, v5
	s_nop 0
	v_pk_mul_f32 v[8:9], v[8:9], v[10:11]
	s_nop 0
	v_cvt_pk_bf16_f32 v7, v8, v9
	v_add_u32_e32 v8, 64, v4
	v_ashrrev_i32_e32 v9, 31, v8
	v_lshlrev_b64 v[8:9], 11, v[8:9]
	v_lshl_add_u64 v[8:9], v[2:3], 0, v[8:9]
	global_store_dwordx2 v[8:9], v[6:7], off
	ds_read_b128 v[6:9], v0 offset:42496
	s_waitcnt lgkmcnt(0)
	v_pk_add_f32 v[6:7], v[6:7], 0 op_sel_hi:[1,0]
	s_nop 0
	v_mul_f32_e32 v5, 0xbfb8aa3b, v6
	v_exp_f32_e32 v5, v5
	v_pk_add_f32 v[8:9], v[8:9], 0 op_sel_hi:[1,0]
	v_add_f32_e32 v5, 1.0, v5
	v_rcp_f32_e32 v10, v5
	v_mul_f32_e32 v5, 0xbfb8aa3b, v7
	v_exp_f32_e32 v5, v5
	s_nop 0
	v_add_f32_e32 v5, 1.0, v5
	v_rcp_f32_e32 v11, v5
	v_mul_f32_e32 v5, 0xbfb8aa3b, v8
	v_exp_f32_e32 v5, v5
	v_pk_mul_f32 v[6:7], v[6:7], v[10:11]
	s_nop 0
	v_cvt_pk_bf16_f32 v6, v6, v7
	v_add_f32_e32 v5, 1.0, v5
	v_rcp_f32_e32 v10, v5
	v_mul_f32_e32 v5, 0xbfb8aa3b, v9
	v_exp_f32_e32 v5, v5
	s_nop 0
	v_add_f32_e32 v5, 1.0, v5
	v_rcp_f32_e32 v11, v5
	s_nop 0
	v_pk_mul_f32 v[8:9], v[8:9], v[10:11]
	s_nop 0
	v_cvt_pk_bf16_f32 v7, v8, v9
	v_add_u32_e32 v8, 0x50, v4
	v_ashrrev_i32_e32 v9, 31, v8
	v_lshlrev_b64 v[8:9], 11, v[8:9]
	v_lshl_add_u64 v[8:9], v[2:3], 0, v[8:9]
	global_store_dwordx2 v[8:9], v[6:7], off
	ds_read_b128 v[6:9], v0 offset:50944
	s_waitcnt lgkmcnt(0)
	v_pk_add_f32 v[6:7], v[6:7], 0 op_sel_hi:[1,0]
	s_nop 0
	v_mul_f32_e32 v5, 0xbfb8aa3b, v6
	v_exp_f32_e32 v5, v5
	v_pk_add_f32 v[8:9], v[8:9], 0 op_sel_hi:[1,0]
	v_add_f32_e32 v5, 1.0, v5
	v_rcp_f32_e32 v10, v5
	v_mul_f32_e32 v5, 0xbfb8aa3b, v7
	v_exp_f32_e32 v5, v5
	s_nop 0
	v_add_f32_e32 v5, 1.0, v5
	v_rcp_f32_e32 v11, v5
	v_mul_f32_e32 v5, 0xbfb8aa3b, v8
	v_exp_f32_e32 v5, v5
	v_pk_mul_f32 v[6:7], v[6:7], v[10:11]
	s_nop 0
	v_cvt_pk_bf16_f32 v6, v6, v7
	v_add_f32_e32 v5, 1.0, v5
	v_rcp_f32_e32 v10, v5
	v_mul_f32_e32 v5, 0xbfb8aa3b, v9
	v_exp_f32_e32 v5, v5
	s_nop 0
	v_add_f32_e32 v5, 1.0, v5
	v_rcp_f32_e32 v11, v5
	s_nop 0
	v_pk_mul_f32 v[8:9], v[8:9], v[10:11]
	s_nop 0
	v_cvt_pk_bf16_f32 v7, v8, v9
	v_add_u32_e32 v8, 0x60, v4
	v_ashrrev_i32_e32 v9, 31, v8
	v_lshlrev_b64 v[8:9], 11, v[8:9]
	v_lshl_add_u64 v[8:9], v[2:3], 0, v[8:9]
	global_store_dwordx2 v[8:9], v[6:7], off
	ds_read_b128 v[6:9], v0 offset:59392
	v_add_u32_e32 v4, 0x70, v4
	v_ashrrev_i32_e32 v5, 31, v4
	v_lshlrev_b64 v[4:5], 11, v[4:5]
	v_lshl_add_u64 v[2:3], v[2:3], 0, v[4:5]
	s_waitcnt lgkmcnt(0)
	v_pk_add_f32 v[6:7], v[6:7], 0 op_sel_hi:[1,0]
	v_pk_add_f32 v[8:9], v[8:9], 0 op_sel_hi:[1,0]
	v_mul_f32_e32 v0, 0xbfb8aa3b, v6
	v_exp_f32_e32 v0, v0
	s_nop 0
	v_add_f32_e32 v0, 1.0, v0
	v_rcp_f32_e32 v10, v0
	v_mul_f32_e32 v0, 0xbfb8aa3b, v7
	v_exp_f32_e32 v0, v0
	s_nop 0
	v_add_f32_e32 v0, 1.0, v0
	v_rcp_f32_e32 v11, v0
	v_mul_f32_e32 v0, 0xbfb8aa3b, v8
	v_exp_f32_e32 v0, v0
	v_pk_mul_f32 v[6:7], v[6:7], v[10:11]
	s_nop 0
	v_cvt_pk_bf16_f32 v6, v6, v7
	v_add_f32_e32 v0, 1.0, v0
	v_rcp_f32_e32 v10, v0
	v_mul_f32_e32 v0, 0xbfb8aa3b, v9
	v_exp_f32_e32 v0, v0
	s_nop 0
	v_add_f32_e32 v0, 1.0, v0
	v_rcp_f32_e32 v11, v0
	s_nop 0
	v_pk_mul_f32 v[8:9], v[8:9], v[10:11]
	s_nop 0
	v_cvt_pk_bf16_f32 v7, v8, v9
	global_store_dwordx2 v[2:3], v[6:7], off

; #define G_STORE(ST, S, unused) do { char* d_ = smem + (ST) * STAGE; \
;     *(uint4*)(d_ + alo[0]) = S##a0; *(uint4*)(d_ + alo[1]) = S##a1; *(uint4*)(d_ + alo[2]) = S##a2; *(uint4*)(d_ + alo[3]) = S##a3; \
;     *(uint4*)(d_ + blo[0]) = S##b0; *(uint4*)(d_ + blo[1]) = S##b1; \
;     if (NBCH == 4) { *(uint4*)(d_ + blo[NBCH - 2]) = S##b2; *(uint4*)(d_ + blo[NBCH - 1]) = S##b3; } } while (0)
; template <int NJ, class RowA>
; DI void gemm_main(f32x16 (&acc)[2][NJ], const bf16_t* __restrict__ A, RowA rowA, size_t kstrideA, int m0, int Mmax,
;                   const bf16_t* __restrict__ Bt, size_t ldb, int n0, int nk, char* smem) {
;     ...
;   __syncthreads();
;   G_LOAD(x0, 0, 0);
;   G_LOAD(x1, 0, 1);
;   G_STORE(0, x0, 0);
;   __syncthreads();
; #pragma unroll 1
;   for (int kt = 0; kt < nk; kt += 2) {
;     G_LOAD(x0, 0, (kt + 2 < nk ? kt + 2 : nk - 1));
;     G_COMPUTE(0);
;     G_STORE(1, x1, 0);
;     __syncthreads();
;     G_LOAD(x1, 0, (kt + 3 < nk ? kt + 3 : nk - 1));
;     G_COMPUTE(1);
;     G_STORE(0, x0, 0);
;     __syncthreads();
.Lpeel_tail_2149:
	ds_read_b128 v[166:169], v0
	ds_read_b128 v[170:173], v139 offset:18432
	ds_read_b128 v[174:177], v139 offset:23040
	ds_read_b128 v[178:181], v0 offset:4608
	s_add_i32 s1, s0, 4
	s_min_u32 s1, s1, 15
	s_lshl_b32 s14, s1, 7
	v_lshl_add_u64 v[98:99], v[122:123], 0, s[14:15]
	v_lshl_add_u64 v[102:103], v[124:125], 0, s[14:15]
	v_lshl_add_u64 v[106:107], v[126:127], 0, s[14:15]
	v_lshl_add_u64 v[110:111], v[128:129], 0, s[14:15]
	v_lshl_add_u64 v[114:115], v[130:131], 0, s[14:15]
	v_lshl_add_u64 v[118:119], v[132:133], 0, s[14:15]
	s_add_i32 s0, s0, 2
	v_lshl_add_u64 v[158:159], v[134:135], 0, s[14:15]
	v_lshl_add_u64 v[160:161], v[136:137], 0, s[14:15]
	s_setprio 1
	ds_read_b128 v[182:185], v0 offset:32
	ds_read_b128 v[186:189], v139 offset:18464
	ds_read_b128 v[190:193], v139 offset:23072
	ds_read_b128 v[194:197], v0 offset:4640
	s_waitcnt lgkmcnt(4)
	v_mfma_f32_32x32x16_bf16 v[50:65], v[166:169], v[170:173], v[50:65]
	v_mfma_f32_32x32x16_bf16 v[34:49], v[166:169], v[174:177], v[34:49]
	v_mfma_f32_32x32x16_bf16 v[18:33], v[178:181], v[170:173], v[18:33]
	v_mfma_f32_32x32x16_bf16 v[2:17], v[178:181], v[174:177], v[2:17]
	ds_read_b128 v[166:169], v0 offset:64
	ds_read_b128 v[170:173], v139 offset:18496
	ds_read_b128 v[174:177], v139 offset:23104
	ds_read_b128 v[178:181], v0 offset:4672
	s_waitcnt lgkmcnt(4)
	v_mfma_f32_32x32x16_bf16 v[50:65], v[182:185], v[186:189], v[50:65]
	v_mfma_f32_32x32x16_bf16 v[34:49], v[182:185], v[190:193], v[34:49]
	v_mfma_f32_32x32x16_bf16 v[18:33], v[194:197], v[186:189], v[18:33]
	v_mfma_f32_32x32x16_bf16 v[2:17], v[194:197], v[190:193], v[2:17]
	ds_read_b128 v[182:185], v0 offset:96
	ds_read_b128 v[186:189], v139 offset:18528
	ds_read_b128 v[190:193], v139 offset:23136
	ds_read_b128 v[194:197], v0 offset:4704
	s_waitcnt lgkmcnt(4)
	v_mfma_f32_32x32x16_bf16 v[50:65], v[166:169], v[170:173], v[50:65]
	s_waitcnt vmcnt(0)
	ds_write_b128 v138, v[74:77] offset:36864
	v_mfma_f32_32x32x16_bf16 v[34:49], v[166:169], v[174:177], v[34:49]
	ds_write_b128 v140, v[78:81] offset:36864
	v_mfma_f32_32x32x16_bf16 v[18:33], v[178:181], v[170:173], v[18:33]
	ds_write_b128 v142, v[82:85] offset:36864
	v_mfma_f32_32x32x16_bf16 v[2:17], v[178:181], v[174:177], v[2:17]
	ds_write_b128 v144, v[86:89] offset:36864
	s_waitcnt lgkmcnt(4)
	v_mfma_f32_32x32x16_bf16 v[50:65], v[182:185], v[186:189], v[50:65]
	ds_write_b128 v138, v[90:93] offset:55296
	v_mfma_f32_32x32x16_bf16 v[34:49], v[182:185], v[190:193], v[34:49]
	ds_write_b128 v140, v[94:97] offset:55296
	v_mfma_f32_32x32x16_bf16 v[18:33], v[194:197], v[186:189], v[18:33]
	ds_write_b128 v142, v[66:69] offset:55296
	v_mfma_f32_32x32x16_bf16 v[2:17], v[194:197], v[190:193], v[2:17]
	ds_write_b128 v144, v[70:73] offset:55296
	s_setprio 0
	s_min_u32 s1, s0, 12
	s_lshl_b32 s14, s1, 7
	v_lshl_add_u64 v[66:67], v[122:123], 0, s[14:15]
	v_lshl_add_u64 v[68:69], v[124:125], 0, s[14:15]
	v_lshl_add_u64 v[70:71], v[126:127], 0, s[14:15]
	v_lshl_add_u64 v[72:73], v[128:129], 0, s[14:15]
	v_lshl_add_u64 v[90:91], v[130:131], 0, s[14:15]
	v_lshl_add_u64 v[94:95], v[132:133], 0, s[14:15]
	s_waitcnt lgkmcnt(0)
	s_barrier
	ds_read_b128 v[166:169], v0 offset:36864
	ds_read_b128 v[170:173], v139 offset:55296
	ds_read_b128 v[174:177], v139 offset:59904
	ds_read_b128 v[178:181], v0 offset:41472
	v_lshl_add_u64 v[154:155], v[134:135], 0, s[14:15]
	v_lshl_add_u64 v[156:157], v[136:137], 0, s[14:15]
	s_setprio 1
	ds_read_b128 v[182:185], v0 offset:36896
	ds_read_b128 v[186:189], v139 offset:55328
	ds_read_b128 v[190:193], v139 offset:59936
	ds_read_b128 v[194:197], v0 offset:41504
	s_waitcnt lgkmcnt(4)
	v_mfma_f32_32x32x16_bf16 v[50:65], v[166:169], v[170:173], v[50:65]
	v_mfma_f32_32x32x16_bf16 v[34:49], v[166:169], v[174:177], v[34:49]
	v_mfma_f32_32x32x16_bf16 v[18:33], v[178:181], v[170:173], v[18:33]
	v_mfma_f32_32x32x16_bf16 v[2:17], v[178:181], v[174:177], v[2:17]
	ds_read_b128 v[166:169], v0 offset:36928
	ds_read_b128 v[170:173], v139 offset:55360
	ds_read_b128 v[174:177], v139 offset:59968
	ds_read_b128 v[178:181], v0 offset:41536
	s_waitcnt lgkmcnt(4)
	v_mfma_f32_32x32x16_bf16 v[50:65], v[182:185], v[186:189], v[50:65]
	v_mfma_f32_32x32x16_bf16 v[34:49], v[182:185], v[190:193], v[34:49]
	v_mfma_f32_32x32x16_bf16 v[18:33], v[194:197], v[186:189], v[18:33]
	v_mfma_f32_32x32x16_bf16 v[2:17], v[194:197], v[190:193], v[2:17]
	ds_read_b128 v[182:185], v0 offset:36960
	ds_read_b128 v[186:189], v139 offset:55392
	ds_read_b128 v[190:193], v139 offset:60000
	ds_read_b128 v[194:197], v0 offset:41568
	s_waitcnt lgkmcnt(4)
	v_mfma_f32_32x32x16_bf16 v[50:65], v[166:169], v[170:173], v[50:65]
	v_mfma_f32_32x32x16_bf16 v[34:49], v[166:169], v[174:177], v[34:49]
	v_mfma_f32_32x32x16_bf16 v[18:33], v[178:181], v[170:173], v[18:33]
	v_mfma_f32_32x32x16_bf16 v[2:17], v[178:181], v[174:177], v[2:17]
	s_waitcnt lgkmcnt(0)
	v_mfma_f32_32x32x16_bf16 v[50:65], v[182:185], v[186:189], v[50:65]
	v_mfma_f32_32x32x16_bf16 v[34:49], v[182:185], v[190:193], v[34:49]
	v_mfma_f32_32x32x16_bf16 v[18:33], v[194:197], v[186:189], v[18:33]
	v_mfma_f32_32x32x16_bf16 v[2:17], v[194:197], v[190:193], v[2:17]
	s_setprio 0
	s_cmp_lt_u32 s0, 14
	s_waitcnt lgkmcnt(0)
	s_barrier
; #define TIDX (tid_launder())
; DI int crow(int reg, int hh) { return (reg & 3) + 8 * (reg >> 2) + 4 * hh; }
; template <int NJ>
; DI void acc_to_ct(const f32x16 (&acc)[2][NJ], float* Ct) {
;   const int lane = TIDX & 63, wid = TIDX >> 6, wm = wid >> 1, wn = wid & 1;
;   const int r = lane & 31, hh = lane >> 5;
; #pragma unroll
;   for (int i = 0; i < 2; ++i)
; #pragma unroll
;     for (int j = 0; j < NJ; ++j)
; #pragma unroll
;       for (int e = 0; e < 16; ++e) Ct[(wm * 64 + i * 32 + crow(e, hh)) * 132 + wn * 32 * NJ + j * 32 + r] = acc[i][j][e];
;   __syncthreads();
; DI void inproj_tile(const Params& p, int l, int mt, int tn, char* smem) {
;     ...
;   if (tn <= 3) {
;     epi_rownorm(Ct, rn, 64);
;     const float* g = tn < 2 ? p.a_q_norm + l * 64 : p.c_q_norm + l * 64;
;     epi_store64(Ct, 0, rn, 0, g, false, nullptr, p.projA, LDA_A, tn * 128, m0, T_TOK);
;     epi_store64(Ct, 64, rn, 1, g, false, nullptr, p.projA, LDA_A, tn * 128 + 64, m0, T_TOK);
;   } else if (tn == 4) {
;     epi_rownorm(Ct, rn, 128);
;     const float* g = p.a_kv_norm + l * 128;
;     epi_store64(Ct, 0, rn, 0, g, false, nullptr, p.projA, LDA_A, 512, m0, T_TOK);
;     epi_store64(Ct, 64, rn, 1, g + 64, false, nullptr, p.projA, LDA_A, 576, m0, T_TOK);
;   } else if (tn <= 8) {
;     epi_store64(Ct, 0, nullptr, 0, nullptr, false, nullptr, p.projA, LDA_A, tn * 128, m0, T_TOK);
;     epi_store64(Ct, 64, nullptr, 0, nullptr, false, nullptr, p.projA, LDA_A, tn * 128 + 64, m0, T_TOK);
;   } else if (tn == 9) {
;     epi_storeKF(Ct, 0, nullptr, 0, nullptr, p.kidxF + ((size_t)b * 64 + s0 / 32) * 2048);
;     epi_store64(Ct, 64, nullptr, 0, nullptr, false, nullptr, p.projA, LDA_A, tn * 128 + 64, m0, T_TOK);
;   } else if (tn == 10) {
;     epi_rownorm(Ct, rn, 64);
;     epi_store64(Ct, 0, nullptr, 0, nullptr, false, nullptr, p.projA, LDA_A, 1280, m0, T_TOK);
;     epi_storeKF(Ct, 64, rn, 1, p.c_k_norm + (l * 3 + 1) * 64, p.kselF + ((size_t)b * 64 + s0 / 32) * 2048);
;   } else if (tn == 11) {
;     epi_rownorm(Ct, rn, 64);
;     epi_storeKF(Ct, 0, rn, 0, p.c_k_norm + (l * 3 + 2) * 64, p.kwinF + ((size_t)b * 64 + s0 / 32) * 2048);
;     epi_storeVF(Ct, 64, p.vselT + ((size_t)b * 64 + s0 / 32) * 2048);
;   } else if (tn == 12) {
;     epi_storeVF(Ct, 0, p.vwinT + ((size_t)b * 64 + s0 / 32) * 2048);
;     for (int idx = TIDX; idx < 128 * 32; idx += 256) {
	s_setprio 2
	v_mov_b32_e32 v0, v230
	s_waitcnt vmcnt(1)
	v_mov_b32_e32 v66, v230
	v_and_b32_e32 v67, 31, v0
	v_lshrrev_b32_e32 v0, 3, v0
	v_and_b32_e32 v0, 4, v0
	v_lshrrev_b32_e32 v68, 1, v66
	v_and_or_b32 v0, v68, s47, v0
	v_and_or_b32 v66, v66, 64, v67
	v_mul_lo_u32 v0, v0, s79
	v_lshl_add_u32 v0, v66, 2, v0
	ds_write2_b32 v0, v50, v34 offset1:32
	ds_write2_b32 v0, v51, v35 offset0:132 offset1:164
	v_add_u32_e32 v34, 0x400, v0
	ds_write2_b32 v34, v52, v36 offset0:8 offset1:40
	ds_write2_b32 v34, v53, v37 offset0:140 offset1:172
	v_add_u32_e32 v34, 0x1000, v0
	ds_write2_b32 v34, v54, v38 offset0:32 offset1:64
	ds_write2_b32 v34, v55, v39 offset0:164 offset1:196
	v_add_u32_e32 v34, 0x1400, v0
	ds_write2_b32 v34, v56, v40 offset0:40 offset1:72
	ds_write2_b32 v34, v57, v41 offset0:172 offset1:204
	v_add_u32_e32 v34, 0x2000, v0
	ds_write2_b32 v34, v58, v42 offset0:64 offset1:96
	ds_write2_b32 v34, v59, v43 offset0:196 offset1:228
	v_add_u32_e32 v34, 0x2400, v0
	ds_write2_b32 v34, v60, v44 offset0:72 offset1:104
	ds_write2_b32 v34, v61, v45 offset0:204 offset1:236
	v_add_u32_e32 v34, 0x3000, v0
	ds_write2_b32 v34, v62, v46 offset0:96 offset1:128
	v_add_u32_e32 v34, 0x3200, v0
	ds_write2_b32 v34, v63, v47 offset0:100 offset1:132
	v_add_u32_e32 v34, 0x3400, v0
	ds_write2_b32 v34, v64, v48 offset0:104 offset1:136
	v_add_u32_e32 v34, 0x3600, v0
	ds_write2_b32 v34, v65, v49 offset0:108 offset1:140
	v_add_u32_e32 v34, 0x4000, v0
	ds_write2_b32 v34, v18, v2 offset0:128 offset1:160
	v_add_u32_e32 v2, 0x4400, v0
	ds_write2_b32 v2, v19, v3 offset0:4 offset1:36
	ds_write2_b32 v2, v20, v4 offset0:136 offset1:168
	v_add_u32_e32 v2, 0x4800, v0
	ds_write2_b32 v2, v21, v5 offset0:12 offset1:44
	v_add_u32_e32 v2, 0x5000, v0
	ds_write2_b32 v2, v22, v6 offset0:160 offset1:192
	v_add_u32_e32 v2, 0x5400, v0
	ds_write2_b32 v2, v23, v7 offset0:36 offset1:68
	ds_write2_b32 v2, v24, v8 offset0:168 offset1:200
	v_add_u32_e32 v2, 0x5800, v0
	ds_write2_b32 v2, v25, v9 offset0:44 offset1:76
	v_add_u32_e32 v2, 0x6000, v0
	ds_write2_b32 v2, v26, v10 offset0:192 offset1:224
	v_add_u32_e32 v2, 0x6400, v0
	ds_write2_b32 v2, v27, v11 offset0:68 offset1:100
	ds_write2_b32 v2, v28, v12 offset0:200 offset1:232
	v_add_u32_e32 v2, 0x6800, v0
	ds_write2_b32 v2, v29, v13 offset0:76 offset1:108
	v_add_u32_e32 v2, 0x7200, v0
	ds_write2_b32 v2, v30, v14 offset0:96 offset1:128
	v_add_u32_e32 v2, 0x7400, v0
	ds_write2_b32 v2, v31, v15 offset0:100 offset1:132
	v_add_u32_e32 v2, 0x7600, v0
	v_add_u32_e32 v0, 0x7800, v0
	s_cmp_gt_u32 s35, 3
	s_mov_b64 s[0:1], -1
	ds_write2_b32 v2, v32, v16 offset0:104 offset1:136
	ds_write2_b32 v0, v33, v17 offset0:108 offset1:140
	s_waitcnt lgkmcnt(0)
	s_barrier
	s_cbranch_scc0 .LBB0_2277
	s_cmp_lg_u32 s35, 4
	s_cbranch_scc0 .LBB0_2236
	s_cmp_gt_u32 s35, 8
	s_cbranch_scc0 .LBB0_2233
	s_ashr_i32 s0, s2, 6
	s_add_i32 s2, s0, s3
	s_ashr_i32 s0, s13, 31
	s_lshr_b32 s0, s0, 21
	s_add_i32 s0, s13, s0
	s_and_b32 s0, s0, 0xfffff800
	s_sub_i32 s14, s13, s0
	s_mov_b64 s[0:1], -1
	s_mov_b64 s[6:7], 0
	s_cmp_lt_i32 s68, -1
	s_mov_b64 s[4:5], 0
	s_cbranch_scc1 .LBB0_2199
	s_cmp_gt_i32 s68, -1
	s_cbranch_scc0 .LBB0_2169
	s_cmp_eq_u32 s68, 0
	s_mov_b64 s[4:5], -1
	s_cbranch_scc0 .LBB0_2168
	v_mov_b32_e32 v2, v230
	s_movk_i32 s0, 0x400
	s_nop 0
	v_cmp_gt_i32_e32 vcc, s0, v2
	s_and_saveexec_b64 s[0:1], vcc
	s_movk_i32 s36, 0x2ff
	s_cbranch_execz .LBB0_2159
	s_ashr_i32 s3, s2, 31
	s_ashr_i32 s4, s14, 5
	v_readlane_b32 s16, v250, 34
	s_ashr_i32 s5, s4, 31
	s_lshl_b64 s[8:9], s[2:3], 18
	v_readlane_b32 s22, v250, 40
	v_readlane_b32 s23, v250, 41
	s_add_u32 s3, s22, s8
	s_addc_u32 s8, s23, s9
	s_lshl_b64 s[4:5], s[4:5], 12
	s_add_u32 s4, s3, s4
	v_and_b32_e32 v0, 31, v2
	s_addc_u32 s5, s8, s5
	v_lshlrev_b32_e32 v3, 2, v0
	v_lshlrev_b32_e32 v4, 3, v2
	s_mov_b64 s[8:9], 0
	v_readlane_b32 s17, v250, 35
	v_readlane_b32 s18, v250, 36
	v_readlane_b32 s19, v250, 37
	v_readlane_b32 s20, v250, 38
	v_readlane_b32 s21, v250, 39
	v_readlane_b32 s24, v250, 42
	v_readlane_b32 s25, v250, 43
	v_readlane_b32 s26, v250, 44
	v_readlane_b32 s27, v250, 45
	v_readlane_b32 s28, v250, 46
	v_readlane_b32 s29, v250, 47
	v_readlane_b32 s30, v250, 48
	v_readlane_b32 s31, v250, 49

; __global__ void __launch_bounds__(256, 2) mega(Params p, int ph_lo, int ph_hi) {
;     ...
;   for (int ph = ph_lo; ph < ph_hi; ++ph) {
;     const int l = ph / NPH, s = ph % NPH;
;     const int reps = ((DUP_MASK >> s) & 1) ? 2 : 1;
;     for (int rep = 0; rep < reps; ++rep) {
;     if (rep > 0) grid.sync();
;     ...
;     if (ph + 1 < ph_hi && s != 5) grid.sync();
.LBB0_2499:
	s_setprio 0
	v_readlane_b32 s0, v250, 0
	v_readlane_b32 s1, v250, 1
	s_add_i32 s0, s0, 1
	v_writelane_b32 v250, s0, 0
	s_cmp_ge_i32 s0, s1
	s_nop 0
	v_writelane_b32 v250, s1, 1
	s_cselect_b64 s[0:1], -1, 0
	s_cmp_eq_u32 s78, 5
	s_cselect_b64 s[2:3], -1, 0
	s_or_b64 s[2:3], s[0:1], s[2:3]
	s_and_b64 vcc, exec, s[2:3]
	s_cbranch_vccz .LBB0_2500
	s_getpc_b64 s[98:99]
